# EpiProj: one dispatch per tile to straight-line epilogues for the passthrough / silu / silu*scale column tiles (log-gate tiles keep the general code)
# baseline (speedup 1.0000x reference)
;     __device__ __forceinline__ void operator()(const f32x4 (&acc)[2][2][4][2], const Unit& u, int wr, int wc, int fr, int fq) const {
;     ...
;             const int seg = __builtin_amdgcn_readfirstlane(col0 >> 9);
;             float lb[8];
; #pragma unroll
;             for (int i = 0; i < 8; ++i) lb[i] = 0.f;
;             if (seg == 1) {
;                 const int ci = col0 & 511;
; #pragma unroll
;                 for (int i = 0; i < 8; ++i) { const float l0 = lbl[ci + i], l1 = lbl[512 + ci + i]; lb[i] = __builtin_amdgcn_rcpf(1.0f + __expf(l1 - l0)); }
;             }
; #pragma unroll
;             for (int ai = 0; ai < 2; ++ai)
; #pragma unroll
;                 for (int m = 0; m < 4; ++m) {
;                     const int row = row0 + ai * HALF + m * 16; const float rs = rsc ? rsc[row - rbase] : rstd[row];
;                     float v[8];
; #pragma unroll
;                     for (int i = 0; i < 4; ++i) { v[i] = acc[ai][bj][m][0][i] * rs; v[4 + i] = acc[ai][bj][m][1][i] * rs; }
;                     if (seg == 0) {
; #pragma unroll
;                         for (int i = 0; i < 8; ++i) v[i] = v[i] * __builtin_amdgcn_rcpf(1.0f + __expf(-v[i])) * 0.08838834764831845f;
;                     } else if (seg == 1) {
; #pragma unroll
;                         for (int i = 0; i < 8; ++i) { const float s = __builtin_amdgcn_rcpf(1.0f + __expf(-v[i])); v[i] = __logf(lb[i] + (1.0f - lb[i]) * s); }
;                     } else if (seg == 3) {
; #pragma unroll
;                         for (int i = 0; i < 8; ++i) v[i] = v[i] * __builtin_amdgcn_rcpf(1.0f + __expf(-v[i]));
;                     }
.LBB0_117:
	v_subrev_u32_e32 v147, s71, v148
	s_andn2_b64 vcc, exec, s[0:1]
	v_lshl_add_u32 v165, v147, 2, s86
	s_cbranch_vccnz .LBB0_119
	ds_read_b32 v228, v165
	ds_read_b32 v229, v165 offset:64
	ds_read_b32 v230, v165 offset:128
	ds_read_b32 v231, v165 offset:192
	ds_read_b32 v232, v165 offset:512
	ds_read_b32 v233, v165 offset:576
	ds_read_b32 v234, v165 offset:640
	ds_read_b32 v235, v165 offset:704
	s_waitcnt lgkmcnt(0)
	v_mov_b32_e32 v150, v228
	s_cmp_eq_u32 s73, 1
	s_cbranch_scc1 .LBB0_119
	s_cmp_lt_u32 s80, 2
	s_cbranch_scc1 .Lep_siluscale
	s_cmp_eq_u32 s73, 3
	s_cbranch_scc1 .Lep_silu
	s_branch .Lep_pass

; #define PG8_BAR __builtin_amdgcn_s_barrier()
; template <class Epi, class Sched, bool ALIGN_EPI = false, bool SP2 = false>
; __device__ __forceinline__ void gemm_phase(PG8_LAS unsigned char* lds, const Gemm g, const Sched& S, const Epi& E) {
;     ...
;         if constexpr (!Epi::AFTER_DRAIN) { E(acc, cur, wr, wc, fr, fq); S.done(cur); }
;         if (!has_next) break;
; #pragma unroll
;         for (int a = 0; a < 2; ++a)
; #pragma unroll
;             for (int b = 0; b < 2; ++b)
; #pragma unroll
;                 for (int m = 0; m < 4; ++m)
; #pragma unroll
;                     for (int n = 0; n < 2; ++n) acc[a][b][m][n] = (f32x4){0.f, 0.f, 0.f, 0.f};
;         cur = nxt; cA = nA; cB = nB; ++ui;
;         if constexpr (ALIGN_EPI) { if (wr == 1) PG8_BAR; }
.Lep_done:
	s_cbranch_vccnz .LBB0_106
	s_andn2_b64 vcc, exec, s[22:23]
	s_cbranch_vccnz .LBB0_105
	s_barrier
	s_branch .LBB0_105

; __device__ __forceinline__ unsigned cvt_pk_bf16(float lo, float hi) { f32x2 v = {lo, hi}; return __builtin_bit_cast(unsigned, __builtin_convertvector(v, nbf16x2e)); }
;     __device__ __forceinline__ void operator()(const f32x4 (&acc)[2][2][4][2], const Unit& u, int wr, int wc, int fr, int fq) const {
;     ...
;                     const int row = row0 + ai * HALF + m * 16; const float rs = rsc ? rsc[row - rbase] : rstd[row];
;                     float v[8];
; #pragma unroll
;                     for (int i = 0; i < 4; ++i) { v[i] = acc[ai][bj][m][0][i] * rs; v[4 + i] = acc[ai][bj][m][1][i] * rs; }
;                     if (seg == 0) {
; #pragma unroll
;                         for (int i = 0; i < 8; ++i) v[i] = v[i] * __builtin_amdgcn_rcpf(1.0f + __expf(-v[i])) * 0.08838834764831845f;
;                     } else if (seg == 1) {
; #pragma unroll
;                         for (int i = 0; i < 8; ++i) { const float s = __builtin_amdgcn_rcpf(1.0f + __expf(-v[i])); v[i] = __logf(lb[i] + (1.0f - lb[i]) * s); }
;                     } else if (seg == 3) {
; #pragma unroll
;                         for (int i = 0; i < 8; ++i) v[i] = v[i] * __builtin_amdgcn_rcpf(1.0f + __expf(-v[i]));
;                     }
;                     u32x4 w; w.x = cvt_pk_bf16(v[0], v[1]); w.y = cvt_pk_bf16(v[2], v[3]); w.z = cvt_pk_bf16(v[4], v[5]); w.w = cvt_pk_bf16(v[6], v[7]);
;                     *(u32x4*)(O + (size_t)row * 2816 + col0) = w;
.Lep_pass:
	v_mov_b32_e32 v176, v228
	v_mov_b32_e32 v178, v229
	v_mov_b32_e32 v180, v230
	v_mov_b32_e32 v182, v231
	v_mov_b32_e32 v184, v232
	v_mov_b32_e32 v186, v233
	v_mov_b32_e32 v188, v234
	v_mov_b32_e32 v190, v235
	v_mov_b64_e32 v[236:237], s[34:35]
	v_ashrrev_i32_e32 v147, 31, v146
	v_mad_i64_i32 v[236:237], s[0:1], v148, s67, v[236:237]
	v_lshl_add_u64 v[236:237], v[146:147], 1, v[236:237]
	v_mov_b64_e32 v[204:205], v[236:237]
	v_pk_mul_f32 v[126:127], v[126:127], v[176:177] op_sel_hi:[1,0]
	v_pk_mul_f32 v[128:129], v[128:129], v[176:177] op_sel_hi:[1,0]
	v_pk_mul_f32 v[122:123], v[122:123], v[176:177] op_sel_hi:[1,0]
	v_pk_mul_f32 v[124:125], v[124:125], v[176:177] op_sel_hi:[1,0]
	s_nop 0
	v_cvt_pk_bf16_f32 v126, v126, v127
	v_cvt_pk_bf16_f32 v127, v128, v129
	v_cvt_pk_bf16_f32 v128, v122, v123
	v_cvt_pk_bf16_f32 v129, v124, v125
	global_store_dwordx4 v[236:237], v[126:129], off
	v_pk_mul_f32 v[118:119], v[118:119], v[178:179] op_sel_hi:[1,0]
	v_pk_mul_f32 v[120:121], v[120:121], v[178:179] op_sel_hi:[1,0]
	v_pk_mul_f32 v[114:115], v[114:115], v[178:179] op_sel_hi:[1,0]
	v_pk_mul_f32 v[116:117], v[116:117], v[178:179] op_sel_hi:[1,0]
	v_add_co_u32_e32 v236, vcc, 0x16000, v236
	s_nop 1
	v_addc_co_u32_e32 v237, vcc, 0, v237, vcc
	s_nop 0
	v_cvt_pk_bf16_f32 v118, v118, v119
	v_cvt_pk_bf16_f32 v119, v120, v121
	v_cvt_pk_bf16_f32 v120, v114, v115
	v_cvt_pk_bf16_f32 v121, v116, v117
	global_store_dwordx4 v[236:237], v[118:121], off
	v_pk_mul_f32 v[110:111], v[110:111], v[180:181] op_sel_hi:[1,0]
	v_pk_mul_f32 v[112:113], v[112:113], v[180:181] op_sel_hi:[1,0]
	v_pk_mul_f32 v[106:107], v[106:107], v[180:181] op_sel_hi:[1,0]
	v_pk_mul_f32 v[108:109], v[108:109], v[180:181] op_sel_hi:[1,0]
	v_add_co_u32_e32 v236, vcc, 0x16000, v236
	s_nop 1
	v_addc_co_u32_e32 v237, vcc, 0, v237, vcc
	s_nop 0
	v_cvt_pk_bf16_f32 v110, v110, v111
	v_cvt_pk_bf16_f32 v111, v112, v113
	v_cvt_pk_bf16_f32 v112, v106, v107
	v_cvt_pk_bf16_f32 v113, v108, v109
	global_store_dwordx4 v[236:237], v[110:113], off
	v_pk_mul_f32 v[102:103], v[102:103], v[182:183] op_sel_hi:[1,0]
	v_pk_mul_f32 v[104:105], v[104:105], v[182:183] op_sel_hi:[1,0]
	v_pk_mul_f32 v[98:99], v[98:99], v[182:183] op_sel_hi:[1,0]
	v_pk_mul_f32 v[100:101], v[100:101], v[182:183] op_sel_hi:[1,0]
	v_add_co_u32_e32 v236, vcc, 0x16000, v236
	s_nop 1
	v_addc_co_u32_e32 v237, vcc, 0, v237, vcc
	s_nop 0
	v_cvt_pk_bf16_f32 v102, v102, v103
	v_cvt_pk_bf16_f32 v103, v104, v105
	v_cvt_pk_bf16_f32 v104, v98, v99
	v_cvt_pk_bf16_f32 v105, v100, v101
	global_store_dwordx4 v[236:237], v[102:105], off
	v_pk_mul_f32 v[94:95], v[94:95], v[184:185] op_sel_hi:[1,0]
	v_pk_mul_f32 v[96:97], v[96:97], v[184:185] op_sel_hi:[1,0]
	v_pk_mul_f32 v[90:91], v[90:91], v[184:185] op_sel_hi:[1,0]
	v_pk_mul_f32 v[92:93], v[92:93], v[184:185] op_sel_hi:[1,0]
	v_add_co_u32_e32 v236, vcc, 0x6e000, v236
	s_nop 1
	v_addc_co_u32_e32 v237, vcc, 0, v237, vcc
	s_nop 0
	v_cvt_pk_bf16_f32 v94, v94, v95
	v_cvt_pk_bf16_f32 v95, v96, v97
	v_cvt_pk_bf16_f32 v96, v90, v91
	v_cvt_pk_bf16_f32 v97, v92, v93
	global_store_dwordx4 v[236:237], v[94:97], off
	v_pk_mul_f32 v[86:87], v[86:87], v[186:187] op_sel_hi:[1,0]
	v_pk_mul_f32 v[88:89], v[88:89], v[186:187] op_sel_hi:[1,0]
	v_pk_mul_f32 v[82:83], v[82:83], v[186:187] op_sel_hi:[1,0]
	v_pk_mul_f32 v[84:85], v[84:85], v[186:187] op_sel_hi:[1,0]
	v_add_co_u32_e32 v236, vcc, 0x16000, v236
	s_nop 1
	v_addc_co_u32_e32 v237, vcc, 0, v237, vcc
	s_nop 0
	v_cvt_pk_bf16_f32 v86, v86, v87
	v_cvt_pk_bf16_f32 v87, v88, v89
	v_cvt_pk_bf16_f32 v88, v82, v83
	v_cvt_pk_bf16_f32 v89, v84, v85
	global_store_dwordx4 v[236:237], v[86:89], off
	v_pk_mul_f32 v[78:79], v[78:79], v[188:189] op_sel_hi:[1,0]
	v_pk_mul_f32 v[80:81], v[80:81], v[188:189] op_sel_hi:[1,0]
	v_pk_mul_f32 v[74:75], v[74:75], v[188:189] op_sel_hi:[1,0]
	v_pk_mul_f32 v[76:77], v[76:77], v[188:189] op_sel_hi:[1,0]
	v_add_co_u32_e32 v236, vcc, 0x16000, v236
	s_nop 1
	v_addc_co_u32_e32 v237, vcc, 0, v237, vcc
	s_nop 0
	v_cvt_pk_bf16_f32 v78, v78, v79
	v_cvt_pk_bf16_f32 v79, v80, v81
	v_cvt_pk_bf16_f32 v80, v74, v75
	v_cvt_pk_bf16_f32 v81, v76, v77
	global_store_dwordx4 v[236:237], v[78:81], off
	v_pk_mul_f32 v[70:71], v[70:71], v[190:191] op_sel_hi:[1,0]
	v_pk_mul_f32 v[72:73], v[72:73], v[190:191] op_sel_hi:[1,0]
	v_pk_mul_f32 v[66:67], v[66:67], v[190:191] op_sel_hi:[1,0]
	v_pk_mul_f32 v[68:69], v[68:69], v[190:191] op_sel_hi:[1,0]
	v_add_co_u32_e32 v236, vcc, 0x16000, v236
	s_nop 1
	v_addc_co_u32_e32 v237, vcc, 0, v237, vcc
	s_nop 0
	v_cvt_pk_bf16_f32 v70, v70, v71
	v_cvt_pk_bf16_f32 v71, v72, v73
	v_cvt_pk_bf16_f32 v72, v66, v67
	v_cvt_pk_bf16_f32 v73, v68, v69
	global_store_dwordx4 v[236:237], v[70:73], off
	v_pk_mul_f32 v[62:63], v[62:63], v[176:177] op_sel_hi:[1,0]
	v_pk_mul_f32 v[64:65], v[64:65], v[176:177] op_sel_hi:[1,0]
	v_pk_mul_f32 v[58:59], v[58:59], v[176:177] op_sel_hi:[1,0]
	v_pk_mul_f32 v[60:61], v[60:61], v[176:177] op_sel_hi:[1,0]
	v_mov_b64_e32 v[236:237], v[204:205]
	s_nop 0
	v_cvt_pk_bf16_f32 v62, v62, v63
	v_cvt_pk_bf16_f32 v63, v64, v65
	v_cvt_pk_bf16_f32 v64, v58, v59
	v_cvt_pk_bf16_f32 v65, v60, v61
	global_store_dwordx4 v[236:237], v[62:65], off offset:256
	v_pk_mul_f32 v[54:55], v[54:55], v[178:179] op_sel_hi:[1,0]
	v_pk_mul_f32 v[56:57], v[56:57], v[178:179] op_sel_hi:[1,0]
	v_pk_mul_f32 v[50:51], v[50:51], v[178:179] op_sel_hi:[1,0]
	v_pk_mul_f32 v[52:53], v[52:53], v[178:179] op_sel_hi:[1,0]
	v_add_co_u32_e32 v236, vcc, 0x16000, v236
	s_nop 1
	v_addc_co_u32_e32 v237, vcc, 0, v237, vcc
	s_nop 0
	v_cvt_pk_bf16_f32 v54, v54, v55
	v_cvt_pk_bf16_f32 v55, v56, v57
	v_cvt_pk_bf16_f32 v56, v50, v51
	v_cvt_pk_bf16_f32 v57, v52, v53
; __device__ __forceinline__ unsigned cvt_pk_bf16(float lo, float hi) { f32x2 v = {lo, hi}; return __builtin_bit_cast(unsigned, __builtin_convertvector(v, nbf16x2e)); }
;     __device__ __forceinline__ void operator()(const f32x4 (&acc)[2][2][4][2], const Unit& u, int wr, int wc, int fr, int fq) const {
;     ...
;                     const int row = row0 + ai * HALF + m * 16; const float rs = rsc ? rsc[row - rbase] : rstd[row];
;                     float v[8];
; #pragma unroll
;                     for (int i = 0; i < 4; ++i) { v[i] = acc[ai][bj][m][0][i] * rs; v[4 + i] = acc[ai][bj][m][1][i] * rs; }
;                     if (seg == 0) {
; #pragma unroll
;                         for (int i = 0; i < 8; ++i) v[i] = v[i] * __builtin_amdgcn_rcpf(1.0f + __expf(-v[i])) * 0.08838834764831845f;
;                     } else if (seg == 1) {
; #pragma unroll
;                         for (int i = 0; i < 8; ++i) { const float s = __builtin_amdgcn_rcpf(1.0f + __expf(-v[i])); v[i] = __logf(lb[i] + (1.0f - lb[i]) * s); }
;                     } else if (seg == 3) {
; #pragma unroll
;                         for (int i = 0; i < 8; ++i) v[i] = v[i] * __builtin_amdgcn_rcpf(1.0f + __expf(-v[i]));
;                     }
;                     u32x4 w; w.x = cvt_pk_bf16(v[0], v[1]); w.y = cvt_pk_bf16(v[2], v[3]); w.z = cvt_pk_bf16(v[4], v[5]); w.w = cvt_pk_bf16(v[6], v[7]);
;                     *(u32x4*)(O + (size_t)row * 2816 + col0) = w;
	global_store_dwordx4 v[236:237], v[54:57], off offset:256
	v_pk_mul_f32 v[46:47], v[46:47], v[180:181] op_sel_hi:[1,0]
	v_pk_mul_f32 v[48:49], v[48:49], v[180:181] op_sel_hi:[1,0]
	v_pk_mul_f32 v[42:43], v[42:43], v[180:181] op_sel_hi:[1,0]
	v_pk_mul_f32 v[44:45], v[44:45], v[180:181] op_sel_hi:[1,0]
	v_add_co_u32_e32 v236, vcc, 0x16000, v236
	s_nop 1
	v_addc_co_u32_e32 v237, vcc, 0, v237, vcc
	s_nop 0
	v_cvt_pk_bf16_f32 v46, v46, v47
	v_cvt_pk_bf16_f32 v47, v48, v49
	v_cvt_pk_bf16_f32 v48, v42, v43
	v_cvt_pk_bf16_f32 v49, v44, v45
	global_store_dwordx4 v[236:237], v[46:49], off offset:256
	v_pk_mul_f32 v[38:39], v[38:39], v[182:183] op_sel_hi:[1,0]
	v_pk_mul_f32 v[40:41], v[40:41], v[182:183] op_sel_hi:[1,0]
	v_pk_mul_f32 v[34:35], v[34:35], v[182:183] op_sel_hi:[1,0]
	v_pk_mul_f32 v[36:37], v[36:37], v[182:183] op_sel_hi:[1,0]
	v_add_co_u32_e32 v236, vcc, 0x16000, v236
	s_nop 1
	v_addc_co_u32_e32 v237, vcc, 0, v237, vcc
	s_nop 0
	v_cvt_pk_bf16_f32 v38, v38, v39
	v_cvt_pk_bf16_f32 v39, v40, v41
	v_cvt_pk_bf16_f32 v40, v34, v35
	v_cvt_pk_bf16_f32 v41, v36, v37
	global_store_dwordx4 v[236:237], v[38:41], off offset:256
	v_pk_mul_f32 v[30:31], v[30:31], v[184:185] op_sel_hi:[1,0]
	v_pk_mul_f32 v[32:33], v[32:33], v[184:185] op_sel_hi:[1,0]
	v_pk_mul_f32 v[26:27], v[26:27], v[184:185] op_sel_hi:[1,0]
	v_pk_mul_f32 v[28:29], v[28:29], v[184:185] op_sel_hi:[1,0]
	v_add_co_u32_e32 v236, vcc, 0x6e000, v236
	s_nop 1
	v_addc_co_u32_e32 v237, vcc, 0, v237, vcc
	s_nop 0
	v_cvt_pk_bf16_f32 v30, v30, v31
	v_cvt_pk_bf16_f32 v31, v32, v33
	v_cvt_pk_bf16_f32 v32, v26, v27
	v_cvt_pk_bf16_f32 v33, v28, v29
	global_store_dwordx4 v[236:237], v[30:33], off offset:256
	v_pk_mul_f32 v[22:23], v[22:23], v[186:187] op_sel_hi:[1,0]
	v_pk_mul_f32 v[24:25], v[24:25], v[186:187] op_sel_hi:[1,0]
	v_pk_mul_f32 v[18:19], v[18:19], v[186:187] op_sel_hi:[1,0]
	v_pk_mul_f32 v[20:21], v[20:21], v[186:187] op_sel_hi:[1,0]
	v_add_co_u32_e32 v236, vcc, 0x16000, v236
	s_nop 1
	v_addc_co_u32_e32 v237, vcc, 0, v237, vcc
	s_nop 0
	v_cvt_pk_bf16_f32 v22, v22, v23
	v_cvt_pk_bf16_f32 v23, v24, v25
	v_cvt_pk_bf16_f32 v24, v18, v19
	v_cvt_pk_bf16_f32 v25, v20, v21
	global_store_dwordx4 v[236:237], v[22:25], off offset:256
	v_pk_mul_f32 v[14:15], v[14:15], v[188:189] op_sel_hi:[1,0]
	v_pk_mul_f32 v[16:17], v[16:17], v[188:189] op_sel_hi:[1,0]
	v_pk_mul_f32 v[10:11], v[10:11], v[188:189] op_sel_hi:[1,0]
	v_pk_mul_f32 v[12:13], v[12:13], v[188:189] op_sel_hi:[1,0]
	v_add_co_u32_e32 v236, vcc, 0x16000, v236
	s_nop 1
	v_addc_co_u32_e32 v237, vcc, 0, v237, vcc
	s_nop 0
	v_cvt_pk_bf16_f32 v14, v14, v15
	v_cvt_pk_bf16_f32 v15, v16, v17
	v_cvt_pk_bf16_f32 v16, v10, v11
	v_cvt_pk_bf16_f32 v17, v12, v13
	global_store_dwordx4 v[236:237], v[14:17], off offset:256
	v_pk_mul_f32 v[6:7], v[6:7], v[190:191] op_sel_hi:[1,0]
	v_pk_mul_f32 v[8:9], v[8:9], v[190:191] op_sel_hi:[1,0]
	v_pk_mul_f32 v[2:3], v[2:3], v[190:191] op_sel_hi:[1,0]
	v_pk_mul_f32 v[4:5], v[4:5], v[190:191] op_sel_hi:[1,0]
	v_add_co_u32_e32 v236, vcc, 0x16000, v236
	s_nop 1
	v_addc_co_u32_e32 v237, vcc, 0, v237, vcc
	s_nop 0
	v_cvt_pk_bf16_f32 v6, v6, v7
	v_cvt_pk_bf16_f32 v7, v8, v9
	v_cvt_pk_bf16_f32 v8, v2, v3
	v_cvt_pk_bf16_f32 v9, v4, v5
	global_store_dwordx4 v[236:237], v[6:9], off offset:256
	s_andn2_b64 vcc, exec, s[4:5]
	s_mov_b64 s[0:1], -1
	s_branch .Lep_done
.Lep_silu:
	v_mov_b32_e32 v176, v228
	v_mov_b32_e32 v178, v229
	v_mov_b32_e32 v180, v230
	v_mov_b32_e32 v182, v231
	v_mov_b32_e32 v184, v232
	v_mov_b32_e32 v186, v233
	v_mov_b32_e32 v188, v234
	v_mov_b32_e32 v190, v235
	v_mov_b64_e32 v[236:237], s[34:35]
	v_ashrrev_i32_e32 v147, 31, v146
	v_mad_i64_i32 v[236:237], s[0:1], v148, s67, v[236:237]
	v_lshl_add_u64 v[236:237], v[146:147], 1, v[236:237]
	v_mov_b64_e32 v[204:205], v[236:237]
	v_pk_mul_f32 v[126:127], v[126:127], v[176:177] op_sel_hi:[1,0]
	v_pk_mul_f32 v[128:129], v[128:129], v[176:177] op_sel_hi:[1,0]
	v_pk_mul_f32 v[122:123], v[122:123], v[176:177] op_sel_hi:[1,0]
	v_pk_mul_f32 v[124:125], v[124:125], v[176:177] op_sel_hi:[1,0]
	v_pk_mul_f32 v[192:193], v[126:127], s[100:101] op_sel_hi:[1,0]
	v_pk_mul_f32 v[194:195], v[128:129], s[100:101] op_sel_hi:[1,0]
	v_pk_mul_f32 v[196:197], v[122:123], s[100:101] op_sel_hi:[1,0]
	v_pk_mul_f32 v[198:199], v[124:125], s[100:101] op_sel_hi:[1,0]
	v_exp_f32_e32 v192, v192
	v_exp_f32_e32 v193, v193
	v_exp_f32_e32 v194, v194
	v_exp_f32_e32 v195, v195
	v_exp_f32_e32 v196, v196
	v_exp_f32_e32 v197, v197
	v_exp_f32_e32 v198, v198
	v_exp_f32_e32 v199, v199
	v_pk_add_f32 v[192:193], v[192:193], s[98:99] op_sel_hi:[1,0]
	v_pk_add_f32 v[194:195], v[194:195], s[98:99] op_sel_hi:[1,0]
	v_pk_add_f32 v[196:197], v[196:197], s[98:99] op_sel_hi:[1,0]
	v_pk_add_f32 v[198:199], v[198:199], s[98:99] op_sel_hi:[1,0]
	v_rcp_f32_e32 v192, v192
	v_rcp_f32_e32 v193, v193
	v_rcp_f32_e32 v194, v194
	v_rcp_f32_e32 v195, v195
	v_rcp_f32_e32 v196, v196
	v_rcp_f32_e32 v197, v197
	v_rcp_f32_e32 v198, v198
	v_rcp_f32_e32 v199, v199
	v_pk_mul_f32 v[126:127], v[126:127], v[192:193]
	v_pk_mul_f32 v[128:129], v[128:129], v[194:195]
	v_pk_mul_f32 v[122:123], v[122:123], v[196:197]
	v_pk_mul_f32 v[124:125], v[124:125], v[198:199]
	v_cvt_pk_bf16_f32 v126, v126, v127
	v_cvt_pk_bf16_f32 v127, v128, v129
	v_cvt_pk_bf16_f32 v128, v122, v123
	v_cvt_pk_bf16_f32 v129, v124, v125
	global_store_dwordx4 v[236:237], v[126:129], off
	v_pk_mul_f32 v[118:119], v[118:119], v[178:179] op_sel_hi:[1,0]
	v_pk_mul_f32 v[120:121], v[120:121], v[178:179] op_sel_hi:[1,0]
	v_pk_mul_f32 v[114:115], v[114:115], v[178:179] op_sel_hi:[1,0]
	v_pk_mul_f32 v[116:117], v[116:117], v[178:179] op_sel_hi:[1,0]
	v_add_co_u32_e32 v236, vcc, 0x16000, v236
; __device__ __forceinline__ unsigned cvt_pk_bf16(float lo, float hi) { f32x2 v = {lo, hi}; return __builtin_bit_cast(unsigned, __builtin_convertvector(v, nbf16x2e)); }
;     __device__ __forceinline__ void operator()(const f32x4 (&acc)[2][2][4][2], const Unit& u, int wr, int wc, int fr, int fq) const {
;     ...
;                     const int row = row0 + ai * HALF + m * 16; const float rs = rsc ? rsc[row - rbase] : rstd[row];
;                     float v[8];
; #pragma unroll
;                     for (int i = 0; i < 4; ++i) { v[i] = acc[ai][bj][m][0][i] * rs; v[4 + i] = acc[ai][bj][m][1][i] * rs; }
;                     if (seg == 0) {
; #pragma unroll
;                         for (int i = 0; i < 8; ++i) v[i] = v[i] * __builtin_amdgcn_rcpf(1.0f + __expf(-v[i])) * 0.08838834764831845f;
;                     } else if (seg == 1) {
; #pragma unroll
;                         for (int i = 0; i < 8; ++i) { const float s = __builtin_amdgcn_rcpf(1.0f + __expf(-v[i])); v[i] = __logf(lb[i] + (1.0f - lb[i]) * s); }
;                     } else if (seg == 3) {
; #pragma unroll
;                         for (int i = 0; i < 8; ++i) v[i] = v[i] * __builtin_amdgcn_rcpf(1.0f + __expf(-v[i]));
;                     }
;                     u32x4 w; w.x = cvt_pk_bf16(v[0], v[1]); w.y = cvt_pk_bf16(v[2], v[3]); w.z = cvt_pk_bf16(v[4], v[5]); w.w = cvt_pk_bf16(v[6], v[7]);
;                     *(u32x4*)(O + (size_t)row * 2816 + col0) = w;
	s_nop 1
	v_addc_co_u32_e32 v237, vcc, 0, v237, vcc
	v_pk_mul_f32 v[192:193], v[118:119], s[100:101] op_sel_hi:[1,0]
	v_pk_mul_f32 v[194:195], v[120:121], s[100:101] op_sel_hi:[1,0]
	v_pk_mul_f32 v[196:197], v[114:115], s[100:101] op_sel_hi:[1,0]
	v_pk_mul_f32 v[198:199], v[116:117], s[100:101] op_sel_hi:[1,0]
	v_exp_f32_e32 v192, v192
	v_exp_f32_e32 v193, v193
	v_exp_f32_e32 v194, v194
	v_exp_f32_e32 v195, v195
	v_exp_f32_e32 v196, v196
	v_exp_f32_e32 v197, v197
	v_exp_f32_e32 v198, v198
	v_exp_f32_e32 v199, v199
	v_pk_add_f32 v[192:193], v[192:193], s[98:99] op_sel_hi:[1,0]
	v_pk_add_f32 v[194:195], v[194:195], s[98:99] op_sel_hi:[1,0]
	v_pk_add_f32 v[196:197], v[196:197], s[98:99] op_sel_hi:[1,0]
	v_pk_add_f32 v[198:199], v[198:199], s[98:99] op_sel_hi:[1,0]
	v_rcp_f32_e32 v192, v192
	v_rcp_f32_e32 v193, v193
	v_rcp_f32_e32 v194, v194
	v_rcp_f32_e32 v195, v195
	v_rcp_f32_e32 v196, v196
	v_rcp_f32_e32 v197, v197
	v_rcp_f32_e32 v198, v198
	v_rcp_f32_e32 v199, v199
	v_pk_mul_f32 v[118:119], v[118:119], v[192:193]
	v_pk_mul_f32 v[120:121], v[120:121], v[194:195]
	v_pk_mul_f32 v[114:115], v[114:115], v[196:197]
	v_pk_mul_f32 v[116:117], v[116:117], v[198:199]
	v_cvt_pk_bf16_f32 v118, v118, v119
	v_cvt_pk_bf16_f32 v119, v120, v121
	v_cvt_pk_bf16_f32 v120, v114, v115
	v_cvt_pk_bf16_f32 v121, v116, v117
	global_store_dwordx4 v[236:237], v[118:121], off
	v_pk_mul_f32 v[110:111], v[110:111], v[180:181] op_sel_hi:[1,0]
	v_pk_mul_f32 v[112:113], v[112:113], v[180:181] op_sel_hi:[1,0]
	v_pk_mul_f32 v[106:107], v[106:107], v[180:181] op_sel_hi:[1,0]
	v_pk_mul_f32 v[108:109], v[108:109], v[180:181] op_sel_hi:[1,0]
	v_add_co_u32_e32 v236, vcc, 0x16000, v236
	s_nop 1
	v_addc_co_u32_e32 v237, vcc, 0, v237, vcc
	v_pk_mul_f32 v[192:193], v[110:111], s[100:101] op_sel_hi:[1,0]
	v_pk_mul_f32 v[194:195], v[112:113], s[100:101] op_sel_hi:[1,0]
	v_pk_mul_f32 v[196:197], v[106:107], s[100:101] op_sel_hi:[1,0]
	v_pk_mul_f32 v[198:199], v[108:109], s[100:101] op_sel_hi:[1,0]
	v_exp_f32_e32 v192, v192
	v_exp_f32_e32 v193, v193
	v_exp_f32_e32 v194, v194
	v_exp_f32_e32 v195, v195
	v_exp_f32_e32 v196, v196
	v_exp_f32_e32 v197, v197
	v_exp_f32_e32 v198, v198
	v_exp_f32_e32 v199, v199
	v_pk_add_f32 v[192:193], v[192:193], s[98:99] op_sel_hi:[1,0]
	v_pk_add_f32 v[194:195], v[194:195], s[98:99] op_sel_hi:[1,0]
	v_pk_add_f32 v[196:197], v[196:197], s[98:99] op_sel_hi:[1,0]
	v_pk_add_f32 v[198:199], v[198:199], s[98:99] op_sel_hi:[1,0]
	v_rcp_f32_e32 v192, v192
	v_rcp_f32_e32 v193, v193
	v_rcp_f32_e32 v194, v194
	v_rcp_f32_e32 v195, v195
	v_rcp_f32_e32 v196, v196
	v_rcp_f32_e32 v197, v197
	v_rcp_f32_e32 v198, v198
	v_rcp_f32_e32 v199, v199
	v_pk_mul_f32 v[110:111], v[110:111], v[192:193]
	v_pk_mul_f32 v[112:113], v[112:113], v[194:195]
	v_pk_mul_f32 v[106:107], v[106:107], v[196:197]
	v_pk_mul_f32 v[108:109], v[108:109], v[198:199]
	v_cvt_pk_bf16_f32 v110, v110, v111
	v_cvt_pk_bf16_f32 v111, v112, v113
	v_cvt_pk_bf16_f32 v112, v106, v107
	v_cvt_pk_bf16_f32 v113, v108, v109
	global_store_dwordx4 v[236:237], v[110:113], off
	v_pk_mul_f32 v[102:103], v[102:103], v[182:183] op_sel_hi:[1,0]
	v_pk_mul_f32 v[104:105], v[104:105], v[182:183] op_sel_hi:[1,0]
	v_pk_mul_f32 v[98:99], v[98:99], v[182:183] op_sel_hi:[1,0]
	v_pk_mul_f32 v[100:101], v[100:101], v[182:183] op_sel_hi:[1,0]
	v_add_co_u32_e32 v236, vcc, 0x16000, v236
	s_nop 1
	v_addc_co_u32_e32 v237, vcc, 0, v237, vcc
	v_pk_mul_f32 v[192:193], v[102:103], s[100:101] op_sel_hi:[1,0]
	v_pk_mul_f32 v[194:195], v[104:105], s[100:101] op_sel_hi:[1,0]
	v_pk_mul_f32 v[196:197], v[98:99], s[100:101] op_sel_hi:[1,0]
	v_pk_mul_f32 v[198:199], v[100:101], s[100:101] op_sel_hi:[1,0]
	v_exp_f32_e32 v192, v192
	v_exp_f32_e32 v193, v193
	v_exp_f32_e32 v194, v194
	v_exp_f32_e32 v195, v195
	v_exp_f32_e32 v196, v196
	v_exp_f32_e32 v197, v197
	v_exp_f32_e32 v198, v198
	v_exp_f32_e32 v199, v199
	v_pk_add_f32 v[192:193], v[192:193], s[98:99] op_sel_hi:[1,0]
	v_pk_add_f32 v[194:195], v[194:195], s[98:99] op_sel_hi:[1,0]
	v_pk_add_f32 v[196:197], v[196:197], s[98:99] op_sel_hi:[1,0]
	v_pk_add_f32 v[198:199], v[198:199], s[98:99] op_sel_hi:[1,0]
	v_rcp_f32_e32 v192, v192
	v_rcp_f32_e32 v193, v193
	v_rcp_f32_e32 v194, v194
	v_rcp_f32_e32 v195, v195
	v_rcp_f32_e32 v196, v196
	v_rcp_f32_e32 v197, v197
	v_rcp_f32_e32 v198, v198
	v_rcp_f32_e32 v199, v199
	v_pk_mul_f32 v[102:103], v[102:103], v[192:193]
	v_pk_mul_f32 v[104:105], v[104:105], v[194:195]
	v_pk_mul_f32 v[98:99], v[98:99], v[196:197]
	v_pk_mul_f32 v[100:101], v[100:101], v[198:199]
	v_cvt_pk_bf16_f32 v102, v102, v103
	v_cvt_pk_bf16_f32 v103, v104, v105
	v_cvt_pk_bf16_f32 v104, v98, v99
	v_cvt_pk_bf16_f32 v105, v100, v101
	global_store_dwordx4 v[236:237], v[102:105], off
	v_pk_mul_f32 v[94:95], v[94:95], v[184:185] op_sel_hi:[1,0]
	v_pk_mul_f32 v[96:97], v[96:97], v[184:185] op_sel_hi:[1,0]
	v_pk_mul_f32 v[90:91], v[90:91], v[184:185] op_sel_hi:[1,0]
	v_pk_mul_f32 v[92:93], v[92:93], v[184:185] op_sel_hi:[1,0]
	v_add_co_u32_e32 v236, vcc, 0x6e000, v236
	s_nop 1
	v_addc_co_u32_e32 v237, vcc, 0, v237, vcc
	v_pk_mul_f32 v[192:193], v[94:95], s[100:101] op_sel_hi:[1,0]
	v_pk_mul_f32 v[194:195], v[96:97], s[100:101] op_sel_hi:[1,0]
	v_pk_mul_f32 v[196:197], v[90:91], s[100:101] op_sel_hi:[1,0]
	v_pk_mul_f32 v[198:199], v[92:93], s[100:101] op_sel_hi:[1,0]
	v_exp_f32_e32 v192, v192
	v_exp_f32_e32 v193, v193
	v_exp_f32_e32 v194, v194
	v_exp_f32_e32 v195, v195
	v_exp_f32_e32 v196, v196
	v_exp_f32_e32 v197, v197
	v_exp_f32_e32 v198, v198
	v_exp_f32_e32 v199, v199
	v_pk_add_f32 v[192:193], v[192:193], s[98:99] op_sel_hi:[1,0]
	v_pk_add_f32 v[194:195], v[194:195], s[98:99] op_sel_hi:[1,0]
; __device__ __forceinline__ unsigned cvt_pk_bf16(float lo, float hi) { f32x2 v = {lo, hi}; return __builtin_bit_cast(unsigned, __builtin_convertvector(v, nbf16x2e)); }
;     __device__ __forceinline__ void operator()(const f32x4 (&acc)[2][2][4][2], const Unit& u, int wr, int wc, int fr, int fq) const {
;     ...
;                     const int row = row0 + ai * HALF + m * 16; const float rs = rsc ? rsc[row - rbase] : rstd[row];
;                     float v[8];
; #pragma unroll
;                     for (int i = 0; i < 4; ++i) { v[i] = acc[ai][bj][m][0][i] * rs; v[4 + i] = acc[ai][bj][m][1][i] * rs; }
;                     if (seg == 0) {
; #pragma unroll
;                         for (int i = 0; i < 8; ++i) v[i] = v[i] * __builtin_amdgcn_rcpf(1.0f + __expf(-v[i])) * 0.08838834764831845f;
;                     } else if (seg == 1) {
; #pragma unroll
;                         for (int i = 0; i < 8; ++i) { const float s = __builtin_amdgcn_rcpf(1.0f + __expf(-v[i])); v[i] = __logf(lb[i] + (1.0f - lb[i]) * s); }
;                     } else if (seg == 3) {
; #pragma unroll
;                         for (int i = 0; i < 8; ++i) v[i] = v[i] * __builtin_amdgcn_rcpf(1.0f + __expf(-v[i]));
;                     }
;                     u32x4 w; w.x = cvt_pk_bf16(v[0], v[1]); w.y = cvt_pk_bf16(v[2], v[3]); w.z = cvt_pk_bf16(v[4], v[5]); w.w = cvt_pk_bf16(v[6], v[7]);
;                     *(u32x4*)(O + (size_t)row * 2816 + col0) = w;
	v_pk_add_f32 v[196:197], v[196:197], s[98:99] op_sel_hi:[1,0]
	v_pk_add_f32 v[198:199], v[198:199], s[98:99] op_sel_hi:[1,0]
	v_rcp_f32_e32 v192, v192
	v_rcp_f32_e32 v193, v193
	v_rcp_f32_e32 v194, v194
	v_rcp_f32_e32 v195, v195
	v_rcp_f32_e32 v196, v196
	v_rcp_f32_e32 v197, v197
	v_rcp_f32_e32 v198, v198
	v_rcp_f32_e32 v199, v199
	v_pk_mul_f32 v[94:95], v[94:95], v[192:193]
	v_pk_mul_f32 v[96:97], v[96:97], v[194:195]
	v_pk_mul_f32 v[90:91], v[90:91], v[196:197]
	v_pk_mul_f32 v[92:93], v[92:93], v[198:199]
	v_cvt_pk_bf16_f32 v94, v94, v95
	v_cvt_pk_bf16_f32 v95, v96, v97
	v_cvt_pk_bf16_f32 v96, v90, v91
	v_cvt_pk_bf16_f32 v97, v92, v93
	global_store_dwordx4 v[236:237], v[94:97], off
	v_pk_mul_f32 v[86:87], v[86:87], v[186:187] op_sel_hi:[1,0]
	v_pk_mul_f32 v[88:89], v[88:89], v[186:187] op_sel_hi:[1,0]
	v_pk_mul_f32 v[82:83], v[82:83], v[186:187] op_sel_hi:[1,0]
	v_pk_mul_f32 v[84:85], v[84:85], v[186:187] op_sel_hi:[1,0]
	v_add_co_u32_e32 v236, vcc, 0x16000, v236
	s_nop 1
	v_addc_co_u32_e32 v237, vcc, 0, v237, vcc
	v_pk_mul_f32 v[192:193], v[86:87], s[100:101] op_sel_hi:[1,0]
	v_pk_mul_f32 v[194:195], v[88:89], s[100:101] op_sel_hi:[1,0]
	v_pk_mul_f32 v[196:197], v[82:83], s[100:101] op_sel_hi:[1,0]
	v_pk_mul_f32 v[198:199], v[84:85], s[100:101] op_sel_hi:[1,0]
	v_exp_f32_e32 v192, v192
	v_exp_f32_e32 v193, v193
	v_exp_f32_e32 v194, v194
	v_exp_f32_e32 v195, v195
	v_exp_f32_e32 v196, v196
	v_exp_f32_e32 v197, v197
	v_exp_f32_e32 v198, v198
	v_exp_f32_e32 v199, v199
	v_pk_add_f32 v[192:193], v[192:193], s[98:99] op_sel_hi:[1,0]
	v_pk_add_f32 v[194:195], v[194:195], s[98:99] op_sel_hi:[1,0]
	v_pk_add_f32 v[196:197], v[196:197], s[98:99] op_sel_hi:[1,0]
	v_pk_add_f32 v[198:199], v[198:199], s[98:99] op_sel_hi:[1,0]
	v_rcp_f32_e32 v192, v192
	v_rcp_f32_e32 v193, v193
	v_rcp_f32_e32 v194, v194
	v_rcp_f32_e32 v195, v195
	v_rcp_f32_e32 v196, v196
	v_rcp_f32_e32 v197, v197
	v_rcp_f32_e32 v198, v198
	v_rcp_f32_e32 v199, v199
	v_pk_mul_f32 v[86:87], v[86:87], v[192:193]
	v_pk_mul_f32 v[88:89], v[88:89], v[194:195]
	v_pk_mul_f32 v[82:83], v[82:83], v[196:197]
	v_pk_mul_f32 v[84:85], v[84:85], v[198:199]
	v_cvt_pk_bf16_f32 v86, v86, v87
	v_cvt_pk_bf16_f32 v87, v88, v89
	v_cvt_pk_bf16_f32 v88, v82, v83
	v_cvt_pk_bf16_f32 v89, v84, v85
	global_store_dwordx4 v[236:237], v[86:89], off
	v_pk_mul_f32 v[78:79], v[78:79], v[188:189] op_sel_hi:[1,0]
	v_pk_mul_f32 v[80:81], v[80:81], v[188:189] op_sel_hi:[1,0]
	v_pk_mul_f32 v[74:75], v[74:75], v[188:189] op_sel_hi:[1,0]
	v_pk_mul_f32 v[76:77], v[76:77], v[188:189] op_sel_hi:[1,0]
	v_add_co_u32_e32 v236, vcc, 0x16000, v236
	s_nop 1
	v_addc_co_u32_e32 v237, vcc, 0, v237, vcc
	v_pk_mul_f32 v[192:193], v[78:79], s[100:101] op_sel_hi:[1,0]
	v_pk_mul_f32 v[194:195], v[80:81], s[100:101] op_sel_hi:[1,0]
	v_pk_mul_f32 v[196:197], v[74:75], s[100:101] op_sel_hi:[1,0]
	v_pk_mul_f32 v[198:199], v[76:77], s[100:101] op_sel_hi:[1,0]
	v_exp_f32_e32 v192, v192
	v_exp_f32_e32 v193, v193
	v_exp_f32_e32 v194, v194
	v_exp_f32_e32 v195, v195
	v_exp_f32_e32 v196, v196
	v_exp_f32_e32 v197, v197
	v_exp_f32_e32 v198, v198
	v_exp_f32_e32 v199, v199
	v_pk_add_f32 v[192:193], v[192:193], s[98:99] op_sel_hi:[1,0]
	v_pk_add_f32 v[194:195], v[194:195], s[98:99] op_sel_hi:[1,0]
	v_pk_add_f32 v[196:197], v[196:197], s[98:99] op_sel_hi:[1,0]
	v_pk_add_f32 v[198:199], v[198:199], s[98:99] op_sel_hi:[1,0]
	v_rcp_f32_e32 v192, v192
	v_rcp_f32_e32 v193, v193
	v_rcp_f32_e32 v194, v194
	v_rcp_f32_e32 v195, v195
	v_rcp_f32_e32 v196, v196
	v_rcp_f32_e32 v197, v197
	v_rcp_f32_e32 v198, v198
	v_rcp_f32_e32 v199, v199
	v_pk_mul_f32 v[78:79], v[78:79], v[192:193]
	v_pk_mul_f32 v[80:81], v[80:81], v[194:195]
	v_pk_mul_f32 v[74:75], v[74:75], v[196:197]
	v_pk_mul_f32 v[76:77], v[76:77], v[198:199]
	v_cvt_pk_bf16_f32 v78, v78, v79
	v_cvt_pk_bf16_f32 v79, v80, v81
	v_cvt_pk_bf16_f32 v80, v74, v75
	v_cvt_pk_bf16_f32 v81, v76, v77
	global_store_dwordx4 v[236:237], v[78:81], off
	v_pk_mul_f32 v[70:71], v[70:71], v[190:191] op_sel_hi:[1,0]
	v_pk_mul_f32 v[72:73], v[72:73], v[190:191] op_sel_hi:[1,0]
	v_pk_mul_f32 v[66:67], v[66:67], v[190:191] op_sel_hi:[1,0]
	v_pk_mul_f32 v[68:69], v[68:69], v[190:191] op_sel_hi:[1,0]
	v_add_co_u32_e32 v236, vcc, 0x16000, v236
	s_nop 1
	v_addc_co_u32_e32 v237, vcc, 0, v237, vcc
	v_pk_mul_f32 v[192:193], v[70:71], s[100:101] op_sel_hi:[1,0]
	v_pk_mul_f32 v[194:195], v[72:73], s[100:101] op_sel_hi:[1,0]
	v_pk_mul_f32 v[196:197], v[66:67], s[100:101] op_sel_hi:[1,0]
	v_pk_mul_f32 v[198:199], v[68:69], s[100:101] op_sel_hi:[1,0]
	v_exp_f32_e32 v192, v192
	v_exp_f32_e32 v193, v193
	v_exp_f32_e32 v194, v194
	v_exp_f32_e32 v195, v195
	v_exp_f32_e32 v196, v196
	v_exp_f32_e32 v197, v197
	v_exp_f32_e32 v198, v198
	v_exp_f32_e32 v199, v199
	v_pk_add_f32 v[192:193], v[192:193], s[98:99] op_sel_hi:[1,0]
	v_pk_add_f32 v[194:195], v[194:195], s[98:99] op_sel_hi:[1,0]
	v_pk_add_f32 v[196:197], v[196:197], s[98:99] op_sel_hi:[1,0]
	v_pk_add_f32 v[198:199], v[198:199], s[98:99] op_sel_hi:[1,0]
	v_rcp_f32_e32 v192, v192
	v_rcp_f32_e32 v193, v193
	v_rcp_f32_e32 v194, v194
	v_rcp_f32_e32 v195, v195
	v_rcp_f32_e32 v196, v196
	v_rcp_f32_e32 v197, v197
	v_rcp_f32_e32 v198, v198
	v_rcp_f32_e32 v199, v199
	v_pk_mul_f32 v[70:71], v[70:71], v[192:193]
	v_pk_mul_f32 v[72:73], v[72:73], v[194:195]
	v_pk_mul_f32 v[66:67], v[66:67], v[196:197]
	v_pk_mul_f32 v[68:69], v[68:69], v[198:199]
	v_cvt_pk_bf16_f32 v70, v70, v71
	v_cvt_pk_bf16_f32 v71, v72, v73
	v_cvt_pk_bf16_f32 v72, v66, v67
	v_cvt_pk_bf16_f32 v73, v68, v69
	global_store_dwordx4 v[236:237], v[70:73], off
	v_pk_mul_f32 v[62:63], v[62:63], v[176:177] op_sel_hi:[1,0]
; __device__ __forceinline__ unsigned cvt_pk_bf16(float lo, float hi) { f32x2 v = {lo, hi}; return __builtin_bit_cast(unsigned, __builtin_convertvector(v, nbf16x2e)); }
;     __device__ __forceinline__ void operator()(const f32x4 (&acc)[2][2][4][2], const Unit& u, int wr, int wc, int fr, int fq) const {
;     ...
;                     const int row = row0 + ai * HALF + m * 16; const float rs = rsc ? rsc[row - rbase] : rstd[row];
;                     float v[8];
; #pragma unroll
;                     for (int i = 0; i < 4; ++i) { v[i] = acc[ai][bj][m][0][i] * rs; v[4 + i] = acc[ai][bj][m][1][i] * rs; }
;                     if (seg == 0) {
; #pragma unroll
;                         for (int i = 0; i < 8; ++i) v[i] = v[i] * __builtin_amdgcn_rcpf(1.0f + __expf(-v[i])) * 0.08838834764831845f;
;                     } else if (seg == 1) {
; #pragma unroll
;                         for (int i = 0; i < 8; ++i) { const float s = __builtin_amdgcn_rcpf(1.0f + __expf(-v[i])); v[i] = __logf(lb[i] + (1.0f - lb[i]) * s); }
;                     } else if (seg == 3) {
; #pragma unroll
;                         for (int i = 0; i < 8; ++i) v[i] = v[i] * __builtin_amdgcn_rcpf(1.0f + __expf(-v[i]));
;                     }
;                     u32x4 w; w.x = cvt_pk_bf16(v[0], v[1]); w.y = cvt_pk_bf16(v[2], v[3]); w.z = cvt_pk_bf16(v[4], v[5]); w.w = cvt_pk_bf16(v[6], v[7]);
;                     *(u32x4*)(O + (size_t)row * 2816 + col0) = w;
	v_pk_mul_f32 v[64:65], v[64:65], v[176:177] op_sel_hi:[1,0]
	v_pk_mul_f32 v[58:59], v[58:59], v[176:177] op_sel_hi:[1,0]
	v_pk_mul_f32 v[60:61], v[60:61], v[176:177] op_sel_hi:[1,0]
	v_mov_b64_e32 v[236:237], v[204:205]
	v_pk_mul_f32 v[192:193], v[62:63], s[100:101] op_sel_hi:[1,0]
	v_pk_mul_f32 v[194:195], v[64:65], s[100:101] op_sel_hi:[1,0]
	v_pk_mul_f32 v[196:197], v[58:59], s[100:101] op_sel_hi:[1,0]
	v_pk_mul_f32 v[198:199], v[60:61], s[100:101] op_sel_hi:[1,0]
	v_exp_f32_e32 v192, v192
	v_exp_f32_e32 v193, v193
	v_exp_f32_e32 v194, v194
	v_exp_f32_e32 v195, v195
	v_exp_f32_e32 v196, v196
	v_exp_f32_e32 v197, v197
	v_exp_f32_e32 v198, v198
	v_exp_f32_e32 v199, v199
	v_pk_add_f32 v[192:193], v[192:193], s[98:99] op_sel_hi:[1,0]
	v_pk_add_f32 v[194:195], v[194:195], s[98:99] op_sel_hi:[1,0]
	v_pk_add_f32 v[196:197], v[196:197], s[98:99] op_sel_hi:[1,0]
	v_pk_add_f32 v[198:199], v[198:199], s[98:99] op_sel_hi:[1,0]
	v_rcp_f32_e32 v192, v192
	v_rcp_f32_e32 v193, v193
	v_rcp_f32_e32 v194, v194
	v_rcp_f32_e32 v195, v195
	v_rcp_f32_e32 v196, v196
	v_rcp_f32_e32 v197, v197
	v_rcp_f32_e32 v198, v198
	v_rcp_f32_e32 v199, v199
	v_pk_mul_f32 v[62:63], v[62:63], v[192:193]
	v_pk_mul_f32 v[64:65], v[64:65], v[194:195]
	v_pk_mul_f32 v[58:59], v[58:59], v[196:197]
	v_pk_mul_f32 v[60:61], v[60:61], v[198:199]
	v_cvt_pk_bf16_f32 v62, v62, v63
	v_cvt_pk_bf16_f32 v63, v64, v65
	v_cvt_pk_bf16_f32 v64, v58, v59
	v_cvt_pk_bf16_f32 v65, v60, v61
	global_store_dwordx4 v[236:237], v[62:65], off offset:256
	v_pk_mul_f32 v[54:55], v[54:55], v[178:179] op_sel_hi:[1,0]
	v_pk_mul_f32 v[56:57], v[56:57], v[178:179] op_sel_hi:[1,0]
	v_pk_mul_f32 v[50:51], v[50:51], v[178:179] op_sel_hi:[1,0]
	v_pk_mul_f32 v[52:53], v[52:53], v[178:179] op_sel_hi:[1,0]
	v_add_co_u32_e32 v236, vcc, 0x16000, v236
	s_nop 1
	v_addc_co_u32_e32 v237, vcc, 0, v237, vcc
	v_pk_mul_f32 v[192:193], v[54:55], s[100:101] op_sel_hi:[1,0]
	v_pk_mul_f32 v[194:195], v[56:57], s[100:101] op_sel_hi:[1,0]
	v_pk_mul_f32 v[196:197], v[50:51], s[100:101] op_sel_hi:[1,0]
	v_pk_mul_f32 v[198:199], v[52:53], s[100:101] op_sel_hi:[1,0]
	v_exp_f32_e32 v192, v192
	v_exp_f32_e32 v193, v193
	v_exp_f32_e32 v194, v194
	v_exp_f32_e32 v195, v195
	v_exp_f32_e32 v196, v196
	v_exp_f32_e32 v197, v197
	v_exp_f32_e32 v198, v198
	v_exp_f32_e32 v199, v199
	v_pk_add_f32 v[192:193], v[192:193], s[98:99] op_sel_hi:[1,0]
	v_pk_add_f32 v[194:195], v[194:195], s[98:99] op_sel_hi:[1,0]
	v_pk_add_f32 v[196:197], v[196:197], s[98:99] op_sel_hi:[1,0]
	v_pk_add_f32 v[198:199], v[198:199], s[98:99] op_sel_hi:[1,0]
	v_rcp_f32_e32 v192, v192
	v_rcp_f32_e32 v193, v193
	v_rcp_f32_e32 v194, v194
	v_rcp_f32_e32 v195, v195
	v_rcp_f32_e32 v196, v196
	v_rcp_f32_e32 v197, v197
	v_rcp_f32_e32 v198, v198
	v_rcp_f32_e32 v199, v199
	v_pk_mul_f32 v[54:55], v[54:55], v[192:193]
	v_pk_mul_f32 v[56:57], v[56:57], v[194:195]
	v_pk_mul_f32 v[50:51], v[50:51], v[196:197]
	v_pk_mul_f32 v[52:53], v[52:53], v[198:199]
	v_cvt_pk_bf16_f32 v54, v54, v55
	v_cvt_pk_bf16_f32 v55, v56, v57
	v_cvt_pk_bf16_f32 v56, v50, v51
	v_cvt_pk_bf16_f32 v57, v52, v53
	global_store_dwordx4 v[236:237], v[54:57], off offset:256
	v_pk_mul_f32 v[46:47], v[46:47], v[180:181] op_sel_hi:[1,0]
	v_pk_mul_f32 v[48:49], v[48:49], v[180:181] op_sel_hi:[1,0]
	v_pk_mul_f32 v[42:43], v[42:43], v[180:181] op_sel_hi:[1,0]
	v_pk_mul_f32 v[44:45], v[44:45], v[180:181] op_sel_hi:[1,0]
	v_add_co_u32_e32 v236, vcc, 0x16000, v236
	s_nop 1
	v_addc_co_u32_e32 v237, vcc, 0, v237, vcc
	v_pk_mul_f32 v[192:193], v[46:47], s[100:101] op_sel_hi:[1,0]
	v_pk_mul_f32 v[194:195], v[48:49], s[100:101] op_sel_hi:[1,0]
	v_pk_mul_f32 v[196:197], v[42:43], s[100:101] op_sel_hi:[1,0]
	v_pk_mul_f32 v[198:199], v[44:45], s[100:101] op_sel_hi:[1,0]
	v_exp_f32_e32 v192, v192
	v_exp_f32_e32 v193, v193
	v_exp_f32_e32 v194, v194
	v_exp_f32_e32 v195, v195
	v_exp_f32_e32 v196, v196
	v_exp_f32_e32 v197, v197
	v_exp_f32_e32 v198, v198
	v_exp_f32_e32 v199, v199
	v_pk_add_f32 v[192:193], v[192:193], s[98:99] op_sel_hi:[1,0]
	v_pk_add_f32 v[194:195], v[194:195], s[98:99] op_sel_hi:[1,0]
	v_pk_add_f32 v[196:197], v[196:197], s[98:99] op_sel_hi:[1,0]
	v_pk_add_f32 v[198:199], v[198:199], s[98:99] op_sel_hi:[1,0]
	v_rcp_f32_e32 v192, v192
	v_rcp_f32_e32 v193, v193
	v_rcp_f32_e32 v194, v194
	v_rcp_f32_e32 v195, v195
	v_rcp_f32_e32 v196, v196
	v_rcp_f32_e32 v197, v197
	v_rcp_f32_e32 v198, v198
	v_rcp_f32_e32 v199, v199
	v_pk_mul_f32 v[46:47], v[46:47], v[192:193]
	v_pk_mul_f32 v[48:49], v[48:49], v[194:195]
	v_pk_mul_f32 v[42:43], v[42:43], v[196:197]
	v_pk_mul_f32 v[44:45], v[44:45], v[198:199]
	v_cvt_pk_bf16_f32 v46, v46, v47
	v_cvt_pk_bf16_f32 v47, v48, v49
	v_cvt_pk_bf16_f32 v48, v42, v43
	v_cvt_pk_bf16_f32 v49, v44, v45
	global_store_dwordx4 v[236:237], v[46:49], off offset:256
	v_pk_mul_f32 v[38:39], v[38:39], v[182:183] op_sel_hi:[1,0]
	v_pk_mul_f32 v[40:41], v[40:41], v[182:183] op_sel_hi:[1,0]
	v_pk_mul_f32 v[34:35], v[34:35], v[182:183] op_sel_hi:[1,0]
	v_pk_mul_f32 v[36:37], v[36:37], v[182:183] op_sel_hi:[1,0]
	v_add_co_u32_e32 v236, vcc, 0x16000, v236
	s_nop 1
	v_addc_co_u32_e32 v237, vcc, 0, v237, vcc
	v_pk_mul_f32 v[192:193], v[38:39], s[100:101] op_sel_hi:[1,0]
	v_pk_mul_f32 v[194:195], v[40:41], s[100:101] op_sel_hi:[1,0]
	v_pk_mul_f32 v[196:197], v[34:35], s[100:101] op_sel_hi:[1,0]
	v_pk_mul_f32 v[198:199], v[36:37], s[100:101] op_sel_hi:[1,0]
	v_exp_f32_e32 v192, v192
	v_exp_f32_e32 v193, v193
	v_exp_f32_e32 v194, v194
	v_exp_f32_e32 v195, v195
	v_exp_f32_e32 v196, v196
	v_exp_f32_e32 v197, v197
	v_exp_f32_e32 v198, v198
	v_exp_f32_e32 v199, v199
	v_pk_add_f32 v[192:193], v[192:193], s[98:99] op_sel_hi:[1,0]
; __device__ __forceinline__ unsigned cvt_pk_bf16(float lo, float hi) { f32x2 v = {lo, hi}; return __builtin_bit_cast(unsigned, __builtin_convertvector(v, nbf16x2e)); }
;     __device__ __forceinline__ void operator()(const f32x4 (&acc)[2][2][4][2], const Unit& u, int wr, int wc, int fr, int fq) const {
;     ...
;                     const int row = row0 + ai * HALF + m * 16; const float rs = rsc ? rsc[row - rbase] : rstd[row];
;                     float v[8];
; #pragma unroll
;                     for (int i = 0; i < 4; ++i) { v[i] = acc[ai][bj][m][0][i] * rs; v[4 + i] = acc[ai][bj][m][1][i] * rs; }
;                     if (seg == 0) {
; #pragma unroll
;                         for (int i = 0; i < 8; ++i) v[i] = v[i] * __builtin_amdgcn_rcpf(1.0f + __expf(-v[i])) * 0.08838834764831845f;
;                     } else if (seg == 1) {
; #pragma unroll
;                         for (int i = 0; i < 8; ++i) { const float s = __builtin_amdgcn_rcpf(1.0f + __expf(-v[i])); v[i] = __logf(lb[i] + (1.0f - lb[i]) * s); }
;                     } else if (seg == 3) {
; #pragma unroll
;                         for (int i = 0; i < 8; ++i) v[i] = v[i] * __builtin_amdgcn_rcpf(1.0f + __expf(-v[i]));
;                     }
;                     u32x4 w; w.x = cvt_pk_bf16(v[0], v[1]); w.y = cvt_pk_bf16(v[2], v[3]); w.z = cvt_pk_bf16(v[4], v[5]); w.w = cvt_pk_bf16(v[6], v[7]);
;                     *(u32x4*)(O + (size_t)row * 2816 + col0) = w;
	v_pk_add_f32 v[194:195], v[194:195], s[98:99] op_sel_hi:[1,0]
	v_pk_add_f32 v[196:197], v[196:197], s[98:99] op_sel_hi:[1,0]
	v_pk_add_f32 v[198:199], v[198:199], s[98:99] op_sel_hi:[1,0]
	v_rcp_f32_e32 v192, v192
	v_rcp_f32_e32 v193, v193
	v_rcp_f32_e32 v194, v194
	v_rcp_f32_e32 v195, v195
	v_rcp_f32_e32 v196, v196
	v_rcp_f32_e32 v197, v197
	v_rcp_f32_e32 v198, v198
	v_rcp_f32_e32 v199, v199
	v_pk_mul_f32 v[38:39], v[38:39], v[192:193]
	v_pk_mul_f32 v[40:41], v[40:41], v[194:195]
	v_pk_mul_f32 v[34:35], v[34:35], v[196:197]
	v_pk_mul_f32 v[36:37], v[36:37], v[198:199]
	v_cvt_pk_bf16_f32 v38, v38, v39
	v_cvt_pk_bf16_f32 v39, v40, v41
	v_cvt_pk_bf16_f32 v40, v34, v35
	v_cvt_pk_bf16_f32 v41, v36, v37
	global_store_dwordx4 v[236:237], v[38:41], off offset:256
	v_pk_mul_f32 v[30:31], v[30:31], v[184:185] op_sel_hi:[1,0]
	v_pk_mul_f32 v[32:33], v[32:33], v[184:185] op_sel_hi:[1,0]
	v_pk_mul_f32 v[26:27], v[26:27], v[184:185] op_sel_hi:[1,0]
	v_pk_mul_f32 v[28:29], v[28:29], v[184:185] op_sel_hi:[1,0]
	v_add_co_u32_e32 v236, vcc, 0x6e000, v236
	s_nop 1
	v_addc_co_u32_e32 v237, vcc, 0, v237, vcc
	v_pk_mul_f32 v[192:193], v[30:31], s[100:101] op_sel_hi:[1,0]
	v_pk_mul_f32 v[194:195], v[32:33], s[100:101] op_sel_hi:[1,0]
	v_pk_mul_f32 v[196:197], v[26:27], s[100:101] op_sel_hi:[1,0]
	v_pk_mul_f32 v[198:199], v[28:29], s[100:101] op_sel_hi:[1,0]
	v_exp_f32_e32 v192, v192
	v_exp_f32_e32 v193, v193
	v_exp_f32_e32 v194, v194
	v_exp_f32_e32 v195, v195
	v_exp_f32_e32 v196, v196
	v_exp_f32_e32 v197, v197
	v_exp_f32_e32 v198, v198
	v_exp_f32_e32 v199, v199
	v_pk_add_f32 v[192:193], v[192:193], s[98:99] op_sel_hi:[1,0]
	v_pk_add_f32 v[194:195], v[194:195], s[98:99] op_sel_hi:[1,0]
	v_pk_add_f32 v[196:197], v[196:197], s[98:99] op_sel_hi:[1,0]
	v_pk_add_f32 v[198:199], v[198:199], s[98:99] op_sel_hi:[1,0]
	v_rcp_f32_e32 v192, v192
	v_rcp_f32_e32 v193, v193
	v_rcp_f32_e32 v194, v194
	v_rcp_f32_e32 v195, v195
	v_rcp_f32_e32 v196, v196
	v_rcp_f32_e32 v197, v197
	v_rcp_f32_e32 v198, v198
	v_rcp_f32_e32 v199, v199
	v_pk_mul_f32 v[30:31], v[30:31], v[192:193]
	v_pk_mul_f32 v[32:33], v[32:33], v[194:195]
	v_pk_mul_f32 v[26:27], v[26:27], v[196:197]
	v_pk_mul_f32 v[28:29], v[28:29], v[198:199]
	v_cvt_pk_bf16_f32 v30, v30, v31
	v_cvt_pk_bf16_f32 v31, v32, v33
	v_cvt_pk_bf16_f32 v32, v26, v27
	v_cvt_pk_bf16_f32 v33, v28, v29
	global_store_dwordx4 v[236:237], v[30:33], off offset:256
	v_pk_mul_f32 v[22:23], v[22:23], v[186:187] op_sel_hi:[1,0]
	v_pk_mul_f32 v[24:25], v[24:25], v[186:187] op_sel_hi:[1,0]
	v_pk_mul_f32 v[18:19], v[18:19], v[186:187] op_sel_hi:[1,0]
	v_pk_mul_f32 v[20:21], v[20:21], v[186:187] op_sel_hi:[1,0]
	v_add_co_u32_e32 v236, vcc, 0x16000, v236
	s_nop 1
	v_addc_co_u32_e32 v237, vcc, 0, v237, vcc
	v_pk_mul_f32 v[192:193], v[22:23], s[100:101] op_sel_hi:[1,0]
	v_pk_mul_f32 v[194:195], v[24:25], s[100:101] op_sel_hi:[1,0]
	v_pk_mul_f32 v[196:197], v[18:19], s[100:101] op_sel_hi:[1,0]
	v_pk_mul_f32 v[198:199], v[20:21], s[100:101] op_sel_hi:[1,0]
	v_exp_f32_e32 v192, v192
	v_exp_f32_e32 v193, v193
	v_exp_f32_e32 v194, v194
	v_exp_f32_e32 v195, v195
	v_exp_f32_e32 v196, v196
	v_exp_f32_e32 v197, v197
	v_exp_f32_e32 v198, v198
	v_exp_f32_e32 v199, v199
	v_pk_add_f32 v[192:193], v[192:193], s[98:99] op_sel_hi:[1,0]
	v_pk_add_f32 v[194:195], v[194:195], s[98:99] op_sel_hi:[1,0]
	v_pk_add_f32 v[196:197], v[196:197], s[98:99] op_sel_hi:[1,0]
	v_pk_add_f32 v[198:199], v[198:199], s[98:99] op_sel_hi:[1,0]
	v_rcp_f32_e32 v192, v192
	v_rcp_f32_e32 v193, v193
	v_rcp_f32_e32 v194, v194
	v_rcp_f32_e32 v195, v195
	v_rcp_f32_e32 v196, v196
	v_rcp_f32_e32 v197, v197
	v_rcp_f32_e32 v198, v198
	v_rcp_f32_e32 v199, v199
	v_pk_mul_f32 v[22:23], v[22:23], v[192:193]
	v_pk_mul_f32 v[24:25], v[24:25], v[194:195]
	v_pk_mul_f32 v[18:19], v[18:19], v[196:197]
	v_pk_mul_f32 v[20:21], v[20:21], v[198:199]
	v_cvt_pk_bf16_f32 v22, v22, v23
	v_cvt_pk_bf16_f32 v23, v24, v25
	v_cvt_pk_bf16_f32 v24, v18, v19
	v_cvt_pk_bf16_f32 v25, v20, v21
	global_store_dwordx4 v[236:237], v[22:25], off offset:256
	v_pk_mul_f32 v[14:15], v[14:15], v[188:189] op_sel_hi:[1,0]
	v_pk_mul_f32 v[16:17], v[16:17], v[188:189] op_sel_hi:[1,0]
	v_pk_mul_f32 v[10:11], v[10:11], v[188:189] op_sel_hi:[1,0]
	v_pk_mul_f32 v[12:13], v[12:13], v[188:189] op_sel_hi:[1,0]
	v_add_co_u32_e32 v236, vcc, 0x16000, v236
	s_nop 1
	v_addc_co_u32_e32 v237, vcc, 0, v237, vcc
	v_pk_mul_f32 v[192:193], v[14:15], s[100:101] op_sel_hi:[1,0]
	v_pk_mul_f32 v[194:195], v[16:17], s[100:101] op_sel_hi:[1,0]
	v_pk_mul_f32 v[196:197], v[10:11], s[100:101] op_sel_hi:[1,0]
	v_pk_mul_f32 v[198:199], v[12:13], s[100:101] op_sel_hi:[1,0]
	v_exp_f32_e32 v192, v192
	v_exp_f32_e32 v193, v193
	v_exp_f32_e32 v194, v194
	v_exp_f32_e32 v195, v195
	v_exp_f32_e32 v196, v196
	v_exp_f32_e32 v197, v197
	v_exp_f32_e32 v198, v198
	v_exp_f32_e32 v199, v199
	v_pk_add_f32 v[192:193], v[192:193], s[98:99] op_sel_hi:[1,0]
	v_pk_add_f32 v[194:195], v[194:195], s[98:99] op_sel_hi:[1,0]
	v_pk_add_f32 v[196:197], v[196:197], s[98:99] op_sel_hi:[1,0]
	v_pk_add_f32 v[198:199], v[198:199], s[98:99] op_sel_hi:[1,0]
	v_rcp_f32_e32 v192, v192
	v_rcp_f32_e32 v193, v193
	v_rcp_f32_e32 v194, v194
	v_rcp_f32_e32 v195, v195
	v_rcp_f32_e32 v196, v196
	v_rcp_f32_e32 v197, v197
	v_rcp_f32_e32 v198, v198
	v_rcp_f32_e32 v199, v199
	v_pk_mul_f32 v[14:15], v[14:15], v[192:193]
	v_pk_mul_f32 v[16:17], v[16:17], v[194:195]
	v_pk_mul_f32 v[10:11], v[10:11], v[196:197]
	v_pk_mul_f32 v[12:13], v[12:13], v[198:199]
	v_cvt_pk_bf16_f32 v14, v14, v15
	v_cvt_pk_bf16_f32 v15, v16, v17
	v_cvt_pk_bf16_f32 v16, v10, v11
	v_cvt_pk_bf16_f32 v17, v12, v13
	global_store_dwordx4 v[236:237], v[14:17], off offset:256
; __device__ __forceinline__ unsigned cvt_pk_bf16(float lo, float hi) { f32x2 v = {lo, hi}; return __builtin_bit_cast(unsigned, __builtin_convertvector(v, nbf16x2e)); }
;     __device__ __forceinline__ void operator()(const f32x4 (&acc)[2][2][4][2], const Unit& u, int wr, int wc, int fr, int fq) const {
;     ...
;                     const int row = row0 + ai * HALF + m * 16; const float rs = rsc ? rsc[row - rbase] : rstd[row];
;                     float v[8];
; #pragma unroll
;                     for (int i = 0; i < 4; ++i) { v[i] = acc[ai][bj][m][0][i] * rs; v[4 + i] = acc[ai][bj][m][1][i] * rs; }
;                     if (seg == 0) {
; #pragma unroll
;                         for (int i = 0; i < 8; ++i) v[i] = v[i] * __builtin_amdgcn_rcpf(1.0f + __expf(-v[i])) * 0.08838834764831845f;
;                     } else if (seg == 1) {
; #pragma unroll
;                         for (int i = 0; i < 8; ++i) { const float s = __builtin_amdgcn_rcpf(1.0f + __expf(-v[i])); v[i] = __logf(lb[i] + (1.0f - lb[i]) * s); }
;                     } else if (seg == 3) {
; #pragma unroll
;                         for (int i = 0; i < 8; ++i) v[i] = v[i] * __builtin_amdgcn_rcpf(1.0f + __expf(-v[i]));
;                     }
;                     u32x4 w; w.x = cvt_pk_bf16(v[0], v[1]); w.y = cvt_pk_bf16(v[2], v[3]); w.z = cvt_pk_bf16(v[4], v[5]); w.w = cvt_pk_bf16(v[6], v[7]);
;                     *(u32x4*)(O + (size_t)row * 2816 + col0) = w;
	v_pk_mul_f32 v[6:7], v[6:7], v[190:191] op_sel_hi:[1,0]
	v_pk_mul_f32 v[8:9], v[8:9], v[190:191] op_sel_hi:[1,0]
	v_pk_mul_f32 v[2:3], v[2:3], v[190:191] op_sel_hi:[1,0]
	v_pk_mul_f32 v[4:5], v[4:5], v[190:191] op_sel_hi:[1,0]
	v_add_co_u32_e32 v236, vcc, 0x16000, v236
	s_nop 1
	v_addc_co_u32_e32 v237, vcc, 0, v237, vcc
	v_pk_mul_f32 v[192:193], v[6:7], s[100:101] op_sel_hi:[1,0]
	v_pk_mul_f32 v[194:195], v[8:9], s[100:101] op_sel_hi:[1,0]
	v_pk_mul_f32 v[196:197], v[2:3], s[100:101] op_sel_hi:[1,0]
	v_pk_mul_f32 v[198:199], v[4:5], s[100:101] op_sel_hi:[1,0]
	v_exp_f32_e32 v192, v192
	v_exp_f32_e32 v193, v193
	v_exp_f32_e32 v194, v194
	v_exp_f32_e32 v195, v195
	v_exp_f32_e32 v196, v196
	v_exp_f32_e32 v197, v197
	v_exp_f32_e32 v198, v198
	v_exp_f32_e32 v199, v199
	v_pk_add_f32 v[192:193], v[192:193], s[98:99] op_sel_hi:[1,0]
	v_pk_add_f32 v[194:195], v[194:195], s[98:99] op_sel_hi:[1,0]
	v_pk_add_f32 v[196:197], v[196:197], s[98:99] op_sel_hi:[1,0]
	v_pk_add_f32 v[198:199], v[198:199], s[98:99] op_sel_hi:[1,0]
	v_rcp_f32_e32 v192, v192
	v_rcp_f32_e32 v193, v193
	v_rcp_f32_e32 v194, v194
	v_rcp_f32_e32 v195, v195
	v_rcp_f32_e32 v196, v196
	v_rcp_f32_e32 v197, v197
	v_rcp_f32_e32 v198, v198
	v_rcp_f32_e32 v199, v199
	v_pk_mul_f32 v[6:7], v[6:7], v[192:193]
	v_pk_mul_f32 v[8:9], v[8:9], v[194:195]
	v_pk_mul_f32 v[2:3], v[2:3], v[196:197]
	v_pk_mul_f32 v[4:5], v[4:5], v[198:199]
	v_cvt_pk_bf16_f32 v6, v6, v7
	v_cvt_pk_bf16_f32 v7, v8, v9
	v_cvt_pk_bf16_f32 v8, v2, v3
	v_cvt_pk_bf16_f32 v9, v4, v5
	global_store_dwordx4 v[236:237], v[6:9], off offset:256
	s_andn2_b64 vcc, exec, s[4:5]
	s_mov_b64 s[0:1], -1
	s_branch .Lep_done
.Lep_siluscale:
	v_mov_b32_e32 v176, v228
	v_mov_b32_e32 v178, v229
	v_mov_b32_e32 v180, v230
	v_mov_b32_e32 v182, v231
	v_mov_b32_e32 v184, v232
	v_mov_b32_e32 v186, v233
	v_mov_b32_e32 v188, v234
	v_mov_b32_e32 v190, v235
	v_mov_b64_e32 v[236:237], s[34:35]
	v_ashrrev_i32_e32 v147, 31, v146
	v_mad_i64_i32 v[236:237], s[0:1], v148, s67, v[236:237]
	v_lshl_add_u64 v[236:237], v[146:147], 1, v[236:237]
	v_mov_b64_e32 v[204:205], v[236:237]
	v_pk_mul_f32 v[126:127], v[126:127], v[176:177] op_sel_hi:[1,0]
	v_pk_mul_f32 v[128:129], v[128:129], v[176:177] op_sel_hi:[1,0]
	v_pk_mul_f32 v[122:123], v[122:123], v[176:177] op_sel_hi:[1,0]
	v_pk_mul_f32 v[124:125], v[124:125], v[176:177] op_sel_hi:[1,0]
	v_pk_mul_f32 v[192:193], v[126:127], s[100:101] op_sel_hi:[1,0]
	v_pk_mul_f32 v[194:195], v[128:129], s[100:101] op_sel_hi:[1,0]
	v_pk_mul_f32 v[196:197], v[122:123], s[100:101] op_sel_hi:[1,0]
	v_pk_mul_f32 v[198:199], v[124:125], s[100:101] op_sel_hi:[1,0]
	v_exp_f32_e32 v192, v192
	v_exp_f32_e32 v193, v193
	v_exp_f32_e32 v194, v194
	v_exp_f32_e32 v195, v195
	v_exp_f32_e32 v196, v196
	v_exp_f32_e32 v197, v197
	v_exp_f32_e32 v198, v198
	v_exp_f32_e32 v199, v199
	v_pk_add_f32 v[192:193], v[192:193], s[98:99] op_sel_hi:[1,0]
	v_pk_add_f32 v[194:195], v[194:195], s[98:99] op_sel_hi:[1,0]
	v_pk_add_f32 v[196:197], v[196:197], s[98:99] op_sel_hi:[1,0]
	v_pk_add_f32 v[198:199], v[198:199], s[98:99] op_sel_hi:[1,0]
	v_rcp_f32_e32 v192, v192
	v_rcp_f32_e32 v193, v193
	v_rcp_f32_e32 v194, v194
	v_rcp_f32_e32 v195, v195
	v_rcp_f32_e32 v196, v196
	v_rcp_f32_e32 v197, v197
	v_rcp_f32_e32 v198, v198
	v_rcp_f32_e32 v199, v199
	v_pk_mul_f32 v[126:127], v[126:127], v[192:193]
	v_pk_mul_f32 v[128:129], v[128:129], v[194:195]
	v_pk_mul_f32 v[122:123], v[122:123], v[196:197]
	v_pk_mul_f32 v[124:125], v[124:125], v[198:199]
	v_pk_mul_f32 v[126:127], v[126:127], s[70:71] op_sel_hi:[1,0]
	v_pk_mul_f32 v[128:129], v[128:129], s[70:71] op_sel_hi:[1,0]
	v_pk_mul_f32 v[122:123], v[122:123], s[70:71] op_sel_hi:[1,0]
	v_pk_mul_f32 v[124:125], v[124:125], s[70:71] op_sel_hi:[1,0]
	v_cvt_pk_bf16_f32 v126, v126, v127
	v_cvt_pk_bf16_f32 v127, v128, v129
	v_cvt_pk_bf16_f32 v128, v122, v123
	v_cvt_pk_bf16_f32 v129, v124, v125
	global_store_dwordx4 v[236:237], v[126:129], off
	v_pk_mul_f32 v[118:119], v[118:119], v[178:179] op_sel_hi:[1,0]
	v_pk_mul_f32 v[120:121], v[120:121], v[178:179] op_sel_hi:[1,0]
	v_pk_mul_f32 v[114:115], v[114:115], v[178:179] op_sel_hi:[1,0]
	v_pk_mul_f32 v[116:117], v[116:117], v[178:179] op_sel_hi:[1,0]
	v_add_co_u32_e32 v236, vcc, 0x16000, v236
	s_nop 1
	v_addc_co_u32_e32 v237, vcc, 0, v237, vcc
	v_pk_mul_f32 v[192:193], v[118:119], s[100:101] op_sel_hi:[1,0]
	v_pk_mul_f32 v[194:195], v[120:121], s[100:101] op_sel_hi:[1,0]
	v_pk_mul_f32 v[196:197], v[114:115], s[100:101] op_sel_hi:[1,0]
	v_pk_mul_f32 v[198:199], v[116:117], s[100:101] op_sel_hi:[1,0]
	v_exp_f32_e32 v192, v192
	v_exp_f32_e32 v193, v193
	v_exp_f32_e32 v194, v194
	v_exp_f32_e32 v195, v195
	v_exp_f32_e32 v196, v196
	v_exp_f32_e32 v197, v197
	v_exp_f32_e32 v198, v198
	v_exp_f32_e32 v199, v199
	v_pk_add_f32 v[192:193], v[192:193], s[98:99] op_sel_hi:[1,0]
	v_pk_add_f32 v[194:195], v[194:195], s[98:99] op_sel_hi:[1,0]
	v_pk_add_f32 v[196:197], v[196:197], s[98:99] op_sel_hi:[1,0]
	v_pk_add_f32 v[198:199], v[198:199], s[98:99] op_sel_hi:[1,0]
	v_rcp_f32_e32 v192, v192
	v_rcp_f32_e32 v193, v193
	v_rcp_f32_e32 v194, v194
	v_rcp_f32_e32 v195, v195
	v_rcp_f32_e32 v196, v196
	v_rcp_f32_e32 v197, v197
	v_rcp_f32_e32 v198, v198
	v_rcp_f32_e32 v199, v199
	v_pk_mul_f32 v[118:119], v[118:119], v[192:193]
	v_pk_mul_f32 v[120:121], v[120:121], v[194:195]
	v_pk_mul_f32 v[114:115], v[114:115], v[196:197]
	v_pk_mul_f32 v[116:117], v[116:117], v[198:199]
	v_pk_mul_f32 v[118:119], v[118:119], s[70:71] op_sel_hi:[1,0]
	v_pk_mul_f32 v[120:121], v[120:121], s[70:71] op_sel_hi:[1,0]
	v_pk_mul_f32 v[114:115], v[114:115], s[70:71] op_sel_hi:[1,0]
	v_pk_mul_f32 v[116:117], v[116:117], s[70:71] op_sel_hi:[1,0]
; __device__ __forceinline__ unsigned cvt_pk_bf16(float lo, float hi) { f32x2 v = {lo, hi}; return __builtin_bit_cast(unsigned, __builtin_convertvector(v, nbf16x2e)); }
;     __device__ __forceinline__ void operator()(const f32x4 (&acc)[2][2][4][2], const Unit& u, int wr, int wc, int fr, int fq) const {
;     ...
;                     const int row = row0 + ai * HALF + m * 16; const float rs = rsc ? rsc[row - rbase] : rstd[row];
;                     float v[8];
; #pragma unroll
;                     for (int i = 0; i < 4; ++i) { v[i] = acc[ai][bj][m][0][i] * rs; v[4 + i] = acc[ai][bj][m][1][i] * rs; }
;                     if (seg == 0) {
; #pragma unroll
;                         for (int i = 0; i < 8; ++i) v[i] = v[i] * __builtin_amdgcn_rcpf(1.0f + __expf(-v[i])) * 0.08838834764831845f;
;                     } else if (seg == 1) {
; #pragma unroll
;                         for (int i = 0; i < 8; ++i) { const float s = __builtin_amdgcn_rcpf(1.0f + __expf(-v[i])); v[i] = __logf(lb[i] + (1.0f - lb[i]) * s); }
;                     } else if (seg == 3) {
; #pragma unroll
;                         for (int i = 0; i < 8; ++i) v[i] = v[i] * __builtin_amdgcn_rcpf(1.0f + __expf(-v[i]));
;                     }
;                     u32x4 w; w.x = cvt_pk_bf16(v[0], v[1]); w.y = cvt_pk_bf16(v[2], v[3]); w.z = cvt_pk_bf16(v[4], v[5]); w.w = cvt_pk_bf16(v[6], v[7]);
;                     *(u32x4*)(O + (size_t)row * 2816 + col0) = w;
	v_cvt_pk_bf16_f32 v118, v118, v119
	v_cvt_pk_bf16_f32 v119, v120, v121
	v_cvt_pk_bf16_f32 v120, v114, v115
	v_cvt_pk_bf16_f32 v121, v116, v117
	global_store_dwordx4 v[236:237], v[118:121], off
	v_pk_mul_f32 v[110:111], v[110:111], v[180:181] op_sel_hi:[1,0]
	v_pk_mul_f32 v[112:113], v[112:113], v[180:181] op_sel_hi:[1,0]
	v_pk_mul_f32 v[106:107], v[106:107], v[180:181] op_sel_hi:[1,0]
	v_pk_mul_f32 v[108:109], v[108:109], v[180:181] op_sel_hi:[1,0]
	v_add_co_u32_e32 v236, vcc, 0x16000, v236
	s_nop 1
	v_addc_co_u32_e32 v237, vcc, 0, v237, vcc
	v_pk_mul_f32 v[192:193], v[110:111], s[100:101] op_sel_hi:[1,0]
	v_pk_mul_f32 v[194:195], v[112:113], s[100:101] op_sel_hi:[1,0]
	v_pk_mul_f32 v[196:197], v[106:107], s[100:101] op_sel_hi:[1,0]
	v_pk_mul_f32 v[198:199], v[108:109], s[100:101] op_sel_hi:[1,0]
	v_exp_f32_e32 v192, v192
	v_exp_f32_e32 v193, v193
	v_exp_f32_e32 v194, v194
	v_exp_f32_e32 v195, v195
	v_exp_f32_e32 v196, v196
	v_exp_f32_e32 v197, v197
	v_exp_f32_e32 v198, v198
	v_exp_f32_e32 v199, v199
	v_pk_add_f32 v[192:193], v[192:193], s[98:99] op_sel_hi:[1,0]
	v_pk_add_f32 v[194:195], v[194:195], s[98:99] op_sel_hi:[1,0]
	v_pk_add_f32 v[196:197], v[196:197], s[98:99] op_sel_hi:[1,0]
	v_pk_add_f32 v[198:199], v[198:199], s[98:99] op_sel_hi:[1,0]
	v_rcp_f32_e32 v192, v192
	v_rcp_f32_e32 v193, v193
	v_rcp_f32_e32 v194, v194
	v_rcp_f32_e32 v195, v195
	v_rcp_f32_e32 v196, v196
	v_rcp_f32_e32 v197, v197
	v_rcp_f32_e32 v198, v198
	v_rcp_f32_e32 v199, v199
	v_pk_mul_f32 v[110:111], v[110:111], v[192:193]
	v_pk_mul_f32 v[112:113], v[112:113], v[194:195]
	v_pk_mul_f32 v[106:107], v[106:107], v[196:197]
	v_pk_mul_f32 v[108:109], v[108:109], v[198:199]
	v_pk_mul_f32 v[110:111], v[110:111], s[70:71] op_sel_hi:[1,0]
	v_pk_mul_f32 v[112:113], v[112:113], s[70:71] op_sel_hi:[1,0]
	v_pk_mul_f32 v[106:107], v[106:107], s[70:71] op_sel_hi:[1,0]
	v_pk_mul_f32 v[108:109], v[108:109], s[70:71] op_sel_hi:[1,0]
	v_cvt_pk_bf16_f32 v110, v110, v111
	v_cvt_pk_bf16_f32 v111, v112, v113
	v_cvt_pk_bf16_f32 v112, v106, v107
	v_cvt_pk_bf16_f32 v113, v108, v109
	global_store_dwordx4 v[236:237], v[110:113], off
	v_pk_mul_f32 v[102:103], v[102:103], v[182:183] op_sel_hi:[1,0]
	v_pk_mul_f32 v[104:105], v[104:105], v[182:183] op_sel_hi:[1,0]
	v_pk_mul_f32 v[98:99], v[98:99], v[182:183] op_sel_hi:[1,0]
	v_pk_mul_f32 v[100:101], v[100:101], v[182:183] op_sel_hi:[1,0]
	v_add_co_u32_e32 v236, vcc, 0x16000, v236
	s_nop 1
	v_addc_co_u32_e32 v237, vcc, 0, v237, vcc
	v_pk_mul_f32 v[192:193], v[102:103], s[100:101] op_sel_hi:[1,0]
	v_pk_mul_f32 v[194:195], v[104:105], s[100:101] op_sel_hi:[1,0]
	v_pk_mul_f32 v[196:197], v[98:99], s[100:101] op_sel_hi:[1,0]
	v_pk_mul_f32 v[198:199], v[100:101], s[100:101] op_sel_hi:[1,0]
	v_exp_f32_e32 v192, v192
	v_exp_f32_e32 v193, v193
	v_exp_f32_e32 v194, v194
	v_exp_f32_e32 v195, v195
	v_exp_f32_e32 v196, v196
	v_exp_f32_e32 v197, v197
	v_exp_f32_e32 v198, v198
	v_exp_f32_e32 v199, v199
	v_pk_add_f32 v[192:193], v[192:193], s[98:99] op_sel_hi:[1,0]
	v_pk_add_f32 v[194:195], v[194:195], s[98:99] op_sel_hi:[1,0]
	v_pk_add_f32 v[196:197], v[196:197], s[98:99] op_sel_hi:[1,0]
	v_pk_add_f32 v[198:199], v[198:199], s[98:99] op_sel_hi:[1,0]
	v_rcp_f32_e32 v192, v192
	v_rcp_f32_e32 v193, v193
	v_rcp_f32_e32 v194, v194
	v_rcp_f32_e32 v195, v195
	v_rcp_f32_e32 v196, v196
	v_rcp_f32_e32 v197, v197
	v_rcp_f32_e32 v198, v198
	v_rcp_f32_e32 v199, v199
	v_pk_mul_f32 v[102:103], v[102:103], v[192:193]
	v_pk_mul_f32 v[104:105], v[104:105], v[194:195]
	v_pk_mul_f32 v[98:99], v[98:99], v[196:197]
	v_pk_mul_f32 v[100:101], v[100:101], v[198:199]
	v_pk_mul_f32 v[102:103], v[102:103], s[70:71] op_sel_hi:[1,0]
	v_pk_mul_f32 v[104:105], v[104:105], s[70:71] op_sel_hi:[1,0]
	v_pk_mul_f32 v[98:99], v[98:99], s[70:71] op_sel_hi:[1,0]
	v_pk_mul_f32 v[100:101], v[100:101], s[70:71] op_sel_hi:[1,0]
	v_cvt_pk_bf16_f32 v102, v102, v103
	v_cvt_pk_bf16_f32 v103, v104, v105
	v_cvt_pk_bf16_f32 v104, v98, v99
	v_cvt_pk_bf16_f32 v105, v100, v101
	global_store_dwordx4 v[236:237], v[102:105], off
	v_pk_mul_f32 v[94:95], v[94:95], v[184:185] op_sel_hi:[1,0]
	v_pk_mul_f32 v[96:97], v[96:97], v[184:185] op_sel_hi:[1,0]
	v_pk_mul_f32 v[90:91], v[90:91], v[184:185] op_sel_hi:[1,0]
	v_pk_mul_f32 v[92:93], v[92:93], v[184:185] op_sel_hi:[1,0]
	v_add_co_u32_e32 v236, vcc, 0x6e000, v236
	s_nop 1
	v_addc_co_u32_e32 v237, vcc, 0, v237, vcc
	v_pk_mul_f32 v[192:193], v[94:95], s[100:101] op_sel_hi:[1,0]
	v_pk_mul_f32 v[194:195], v[96:97], s[100:101] op_sel_hi:[1,0]
	v_pk_mul_f32 v[196:197], v[90:91], s[100:101] op_sel_hi:[1,0]
	v_pk_mul_f32 v[198:199], v[92:93], s[100:101] op_sel_hi:[1,0]
	v_exp_f32_e32 v192, v192
	v_exp_f32_e32 v193, v193
	v_exp_f32_e32 v194, v194
	v_exp_f32_e32 v195, v195
	v_exp_f32_e32 v196, v196
	v_exp_f32_e32 v197, v197
	v_exp_f32_e32 v198, v198
	v_exp_f32_e32 v199, v199
	v_pk_add_f32 v[192:193], v[192:193], s[98:99] op_sel_hi:[1,0]
	v_pk_add_f32 v[194:195], v[194:195], s[98:99] op_sel_hi:[1,0]
	v_pk_add_f32 v[196:197], v[196:197], s[98:99] op_sel_hi:[1,0]
	v_pk_add_f32 v[198:199], v[198:199], s[98:99] op_sel_hi:[1,0]
	v_rcp_f32_e32 v192, v192
	v_rcp_f32_e32 v193, v193
	v_rcp_f32_e32 v194, v194
	v_rcp_f32_e32 v195, v195
	v_rcp_f32_e32 v196, v196
	v_rcp_f32_e32 v197, v197
	v_rcp_f32_e32 v198, v198
	v_rcp_f32_e32 v199, v199
	v_pk_mul_f32 v[94:95], v[94:95], v[192:193]
	v_pk_mul_f32 v[96:97], v[96:97], v[194:195]
	v_pk_mul_f32 v[90:91], v[90:91], v[196:197]
	v_pk_mul_f32 v[92:93], v[92:93], v[198:199]
	v_pk_mul_f32 v[94:95], v[94:95], s[70:71] op_sel_hi:[1,0]
	v_pk_mul_f32 v[96:97], v[96:97], s[70:71] op_sel_hi:[1,0]
	v_pk_mul_f32 v[90:91], v[90:91], s[70:71] op_sel_hi:[1,0]
; __device__ __forceinline__ unsigned cvt_pk_bf16(float lo, float hi) { f32x2 v = {lo, hi}; return __builtin_bit_cast(unsigned, __builtin_convertvector(v, nbf16x2e)); }
;     __device__ __forceinline__ void operator()(const f32x4 (&acc)[2][2][4][2], const Unit& u, int wr, int wc, int fr, int fq) const {
;     ...
;                 for (int m = 0; m < 4; ++m) {
;                     const int row = row0 + ai * HALF + m * 16; const float rs = rsc ? rsc[row - rbase] : rstd[row];
;                     float v[8];
; #pragma unroll
;                     for (int i = 0; i < 4; ++i) { v[i] = acc[ai][bj][m][0][i] * rs; v[4 + i] = acc[ai][bj][m][1][i] * rs; }
;                     if (seg == 0) {
; #pragma unroll
;                         for (int i = 0; i < 8; ++i) v[i] = v[i] * __builtin_amdgcn_rcpf(1.0f + __expf(-v[i])) * 0.08838834764831845f;
;                     } else if (seg == 1) {
; #pragma unroll
;                         for (int i = 0; i < 8; ++i) { const float s = __builtin_amdgcn_rcpf(1.0f + __expf(-v[i])); v[i] = __logf(lb[i] + (1.0f - lb[i]) * s); }
;                     } else if (seg == 3) {
; #pragma unroll
;                         for (int i = 0; i < 8; ++i) v[i] = v[i] * __builtin_amdgcn_rcpf(1.0f + __expf(-v[i]));
;                     }
;                     u32x4 w; w.x = cvt_pk_bf16(v[0], v[1]); w.y = cvt_pk_bf16(v[2], v[3]); w.z = cvt_pk_bf16(v[4], v[5]); w.w = cvt_pk_bf16(v[6], v[7]);
;                     *(u32x4*)(O + (size_t)row * 2816 + col0) = w;
	v_pk_mul_f32 v[92:93], v[92:93], s[70:71] op_sel_hi:[1,0]
	v_cvt_pk_bf16_f32 v94, v94, v95
	v_cvt_pk_bf16_f32 v95, v96, v97
	v_cvt_pk_bf16_f32 v96, v90, v91
	v_cvt_pk_bf16_f32 v97, v92, v93
	global_store_dwordx4 v[236:237], v[94:97], off
	v_pk_mul_f32 v[86:87], v[86:87], v[186:187] op_sel_hi:[1,0]
	v_pk_mul_f32 v[88:89], v[88:89], v[186:187] op_sel_hi:[1,0]
	v_pk_mul_f32 v[82:83], v[82:83], v[186:187] op_sel_hi:[1,0]
	v_pk_mul_f32 v[84:85], v[84:85], v[186:187] op_sel_hi:[1,0]
	v_add_co_u32_e32 v236, vcc, 0x16000, v236
	s_nop 1
	v_addc_co_u32_e32 v237, vcc, 0, v237, vcc
	v_pk_mul_f32 v[192:193], v[86:87], s[100:101] op_sel_hi:[1,0]
	v_pk_mul_f32 v[194:195], v[88:89], s[100:101] op_sel_hi:[1,0]
	v_pk_mul_f32 v[196:197], v[82:83], s[100:101] op_sel_hi:[1,0]
	v_pk_mul_f32 v[198:199], v[84:85], s[100:101] op_sel_hi:[1,0]
	v_exp_f32_e32 v192, v192
	v_exp_f32_e32 v193, v193
	v_exp_f32_e32 v194, v194
	v_exp_f32_e32 v195, v195
	v_exp_f32_e32 v196, v196
	v_exp_f32_e32 v197, v197
	v_exp_f32_e32 v198, v198
	v_exp_f32_e32 v199, v199
	v_pk_add_f32 v[192:193], v[192:193], s[98:99] op_sel_hi:[1,0]
	v_pk_add_f32 v[194:195], v[194:195], s[98:99] op_sel_hi:[1,0]
	v_pk_add_f32 v[196:197], v[196:197], s[98:99] op_sel_hi:[1,0]
	v_pk_add_f32 v[198:199], v[198:199], s[98:99] op_sel_hi:[1,0]
	v_rcp_f32_e32 v192, v192
	v_rcp_f32_e32 v193, v193
	v_rcp_f32_e32 v194, v194
	v_rcp_f32_e32 v195, v195
	v_rcp_f32_e32 v196, v196
	v_rcp_f32_e32 v197, v197
	v_rcp_f32_e32 v198, v198
	v_rcp_f32_e32 v199, v199
	v_pk_mul_f32 v[86:87], v[86:87], v[192:193]
	v_pk_mul_f32 v[88:89], v[88:89], v[194:195]
	v_pk_mul_f32 v[82:83], v[82:83], v[196:197]
	v_pk_mul_f32 v[84:85], v[84:85], v[198:199]
	v_pk_mul_f32 v[86:87], v[86:87], s[70:71] op_sel_hi:[1,0]
	v_pk_mul_f32 v[88:89], v[88:89], s[70:71] op_sel_hi:[1,0]
	v_pk_mul_f32 v[82:83], v[82:83], s[70:71] op_sel_hi:[1,0]
	v_pk_mul_f32 v[84:85], v[84:85], s[70:71] op_sel_hi:[1,0]
	v_cvt_pk_bf16_f32 v86, v86, v87
	v_cvt_pk_bf16_f32 v87, v88, v89
	v_cvt_pk_bf16_f32 v88, v82, v83
	v_cvt_pk_bf16_f32 v89, v84, v85
	global_store_dwordx4 v[236:237], v[86:89], off
	v_pk_mul_f32 v[78:79], v[78:79], v[188:189] op_sel_hi:[1,0]
	v_pk_mul_f32 v[80:81], v[80:81], v[188:189] op_sel_hi:[1,0]
	v_pk_mul_f32 v[74:75], v[74:75], v[188:189] op_sel_hi:[1,0]
	v_pk_mul_f32 v[76:77], v[76:77], v[188:189] op_sel_hi:[1,0]
	v_add_co_u32_e32 v236, vcc, 0x16000, v236
	s_nop 1
	v_addc_co_u32_e32 v237, vcc, 0, v237, vcc
	v_pk_mul_f32 v[192:193], v[78:79], s[100:101] op_sel_hi:[1,0]
	v_pk_mul_f32 v[194:195], v[80:81], s[100:101] op_sel_hi:[1,0]
	v_pk_mul_f32 v[196:197], v[74:75], s[100:101] op_sel_hi:[1,0]
	v_pk_mul_f32 v[198:199], v[76:77], s[100:101] op_sel_hi:[1,0]
	v_exp_f32_e32 v192, v192
	v_exp_f32_e32 v193, v193
	v_exp_f32_e32 v194, v194
	v_exp_f32_e32 v195, v195
	v_exp_f32_e32 v196, v196
	v_exp_f32_e32 v197, v197
	v_exp_f32_e32 v198, v198
	v_exp_f32_e32 v199, v199
	v_pk_add_f32 v[192:193], v[192:193], s[98:99] op_sel_hi:[1,0]
	v_pk_add_f32 v[194:195], v[194:195], s[98:99] op_sel_hi:[1,0]
	v_pk_add_f32 v[196:197], v[196:197], s[98:99] op_sel_hi:[1,0]
	v_pk_add_f32 v[198:199], v[198:199], s[98:99] op_sel_hi:[1,0]
	v_rcp_f32_e32 v192, v192
	v_rcp_f32_e32 v193, v193
	v_rcp_f32_e32 v194, v194
	v_rcp_f32_e32 v195, v195
	v_rcp_f32_e32 v196, v196
	v_rcp_f32_e32 v197, v197
	v_rcp_f32_e32 v198, v198
	v_rcp_f32_e32 v199, v199
	v_pk_mul_f32 v[78:79], v[78:79], v[192:193]
	v_pk_mul_f32 v[80:81], v[80:81], v[194:195]
	v_pk_mul_f32 v[74:75], v[74:75], v[196:197]
	v_pk_mul_f32 v[76:77], v[76:77], v[198:199]
	v_pk_mul_f32 v[78:79], v[78:79], s[70:71] op_sel_hi:[1,0]
	v_pk_mul_f32 v[80:81], v[80:81], s[70:71] op_sel_hi:[1,0]
	v_pk_mul_f32 v[74:75], v[74:75], s[70:71] op_sel_hi:[1,0]
	v_pk_mul_f32 v[76:77], v[76:77], s[70:71] op_sel_hi:[1,0]
	v_cvt_pk_bf16_f32 v78, v78, v79
	v_cvt_pk_bf16_f32 v79, v80, v81
	v_cvt_pk_bf16_f32 v80, v74, v75
	v_cvt_pk_bf16_f32 v81, v76, v77
	global_store_dwordx4 v[236:237], v[78:81], off
	v_pk_mul_f32 v[70:71], v[70:71], v[190:191] op_sel_hi:[1,0]
	v_pk_mul_f32 v[72:73], v[72:73], v[190:191] op_sel_hi:[1,0]
	v_pk_mul_f32 v[66:67], v[66:67], v[190:191] op_sel_hi:[1,0]
	v_pk_mul_f32 v[68:69], v[68:69], v[190:191] op_sel_hi:[1,0]
	v_add_co_u32_e32 v236, vcc, 0x16000, v236
	s_nop 1
	v_addc_co_u32_e32 v237, vcc, 0, v237, vcc
	v_pk_mul_f32 v[192:193], v[70:71], s[100:101] op_sel_hi:[1,0]
	v_pk_mul_f32 v[194:195], v[72:73], s[100:101] op_sel_hi:[1,0]
	v_pk_mul_f32 v[196:197], v[66:67], s[100:101] op_sel_hi:[1,0]
	v_pk_mul_f32 v[198:199], v[68:69], s[100:101] op_sel_hi:[1,0]
	v_exp_f32_e32 v192, v192
	v_exp_f32_e32 v193, v193
	v_exp_f32_e32 v194, v194
	v_exp_f32_e32 v195, v195
	v_exp_f32_e32 v196, v196
	v_exp_f32_e32 v197, v197
	v_exp_f32_e32 v198, v198
	v_exp_f32_e32 v199, v199
	v_pk_add_f32 v[192:193], v[192:193], s[98:99] op_sel_hi:[1,0]
	v_pk_add_f32 v[194:195], v[194:195], s[98:99] op_sel_hi:[1,0]
	v_pk_add_f32 v[196:197], v[196:197], s[98:99] op_sel_hi:[1,0]
	v_pk_add_f32 v[198:199], v[198:199], s[98:99] op_sel_hi:[1,0]
	v_rcp_f32_e32 v192, v192
	v_rcp_f32_e32 v193, v193
	v_rcp_f32_e32 v194, v194
	v_rcp_f32_e32 v195, v195
	v_rcp_f32_e32 v196, v196
	v_rcp_f32_e32 v197, v197
	v_rcp_f32_e32 v198, v198
	v_rcp_f32_e32 v199, v199
	v_pk_mul_f32 v[70:71], v[70:71], v[192:193]
	v_pk_mul_f32 v[72:73], v[72:73], v[194:195]
	v_pk_mul_f32 v[66:67], v[66:67], v[196:197]
	v_pk_mul_f32 v[68:69], v[68:69], v[198:199]
	v_pk_mul_f32 v[70:71], v[70:71], s[70:71] op_sel_hi:[1,0]
	v_pk_mul_f32 v[72:73], v[72:73], s[70:71] op_sel_hi:[1,0]
	v_pk_mul_f32 v[66:67], v[66:67], s[70:71] op_sel_hi:[1,0]
	v_pk_mul_f32 v[68:69], v[68:69], s[70:71] op_sel_hi:[1,0]
; __device__ __forceinline__ unsigned cvt_pk_bf16(float lo, float hi) { f32x2 v = {lo, hi}; return __builtin_bit_cast(unsigned, __builtin_convertvector(v, nbf16x2e)); }
;     __device__ __forceinline__ void operator()(const f32x4 (&acc)[2][2][4][2], const Unit& u, int wr, int wc, int fr, int fq) const {
;     ...
;                 for (int m = 0; m < 4; ++m) {
;                     const int row = row0 + ai * HALF + m * 16; const float rs = rsc ? rsc[row - rbase] : rstd[row];
;                     float v[8];
; #pragma unroll
;                     for (int i = 0; i < 4; ++i) { v[i] = acc[ai][bj][m][0][i] * rs; v[4 + i] = acc[ai][bj][m][1][i] * rs; }
;                     if (seg == 0) {
; #pragma unroll
;                         for (int i = 0; i < 8; ++i) v[i] = v[i] * __builtin_amdgcn_rcpf(1.0f + __expf(-v[i])) * 0.08838834764831845f;
;                     } else if (seg == 1) {
; #pragma unroll
;                         for (int i = 0; i < 8; ++i) { const float s = __builtin_amdgcn_rcpf(1.0f + __expf(-v[i])); v[i] = __logf(lb[i] + (1.0f - lb[i]) * s); }
;                     } else if (seg == 3) {
; #pragma unroll
;                         for (int i = 0; i < 8; ++i) v[i] = v[i] * __builtin_amdgcn_rcpf(1.0f + __expf(-v[i]));
;                     }
;                     u32x4 w; w.x = cvt_pk_bf16(v[0], v[1]); w.y = cvt_pk_bf16(v[2], v[3]); w.z = cvt_pk_bf16(v[4], v[5]); w.w = cvt_pk_bf16(v[6], v[7]);
;                     *(u32x4*)(O + (size_t)row * 2816 + col0) = w;
	v_cvt_pk_bf16_f32 v70, v70, v71
	v_cvt_pk_bf16_f32 v71, v72, v73
	v_cvt_pk_bf16_f32 v72, v66, v67
	v_cvt_pk_bf16_f32 v73, v68, v69
	global_store_dwordx4 v[236:237], v[70:73], off
	v_pk_mul_f32 v[62:63], v[62:63], v[176:177] op_sel_hi:[1,0]
	v_pk_mul_f32 v[64:65], v[64:65], v[176:177] op_sel_hi:[1,0]
	v_pk_mul_f32 v[58:59], v[58:59], v[176:177] op_sel_hi:[1,0]
	v_pk_mul_f32 v[60:61], v[60:61], v[176:177] op_sel_hi:[1,0]
	v_mov_b64_e32 v[236:237], v[204:205]
	v_pk_mul_f32 v[192:193], v[62:63], s[100:101] op_sel_hi:[1,0]
	v_pk_mul_f32 v[194:195], v[64:65], s[100:101] op_sel_hi:[1,0]
	v_pk_mul_f32 v[196:197], v[58:59], s[100:101] op_sel_hi:[1,0]
	v_pk_mul_f32 v[198:199], v[60:61], s[100:101] op_sel_hi:[1,0]
	v_exp_f32_e32 v192, v192
	v_exp_f32_e32 v193, v193
	v_exp_f32_e32 v194, v194
	v_exp_f32_e32 v195, v195
	v_exp_f32_e32 v196, v196
	v_exp_f32_e32 v197, v197
	v_exp_f32_e32 v198, v198
	v_exp_f32_e32 v199, v199
	v_pk_add_f32 v[192:193], v[192:193], s[98:99] op_sel_hi:[1,0]
	v_pk_add_f32 v[194:195], v[194:195], s[98:99] op_sel_hi:[1,0]
	v_pk_add_f32 v[196:197], v[196:197], s[98:99] op_sel_hi:[1,0]
	v_pk_add_f32 v[198:199], v[198:199], s[98:99] op_sel_hi:[1,0]
	v_rcp_f32_e32 v192, v192
	v_rcp_f32_e32 v193, v193
	v_rcp_f32_e32 v194, v194
	v_rcp_f32_e32 v195, v195
	v_rcp_f32_e32 v196, v196
	v_rcp_f32_e32 v197, v197
	v_rcp_f32_e32 v198, v198
	v_rcp_f32_e32 v199, v199
	v_pk_mul_f32 v[62:63], v[62:63], v[192:193]
	v_pk_mul_f32 v[64:65], v[64:65], v[194:195]
	v_pk_mul_f32 v[58:59], v[58:59], v[196:197]
	v_pk_mul_f32 v[60:61], v[60:61], v[198:199]
	v_pk_mul_f32 v[62:63], v[62:63], s[70:71] op_sel_hi:[1,0]
	v_pk_mul_f32 v[64:65], v[64:65], s[70:71] op_sel_hi:[1,0]
	v_pk_mul_f32 v[58:59], v[58:59], s[70:71] op_sel_hi:[1,0]
	v_pk_mul_f32 v[60:61], v[60:61], s[70:71] op_sel_hi:[1,0]
	v_cvt_pk_bf16_f32 v62, v62, v63
	v_cvt_pk_bf16_f32 v63, v64, v65
	v_cvt_pk_bf16_f32 v64, v58, v59
	v_cvt_pk_bf16_f32 v65, v60, v61
	global_store_dwordx4 v[236:237], v[62:65], off offset:256
	v_pk_mul_f32 v[54:55], v[54:55], v[178:179] op_sel_hi:[1,0]
	v_pk_mul_f32 v[56:57], v[56:57], v[178:179] op_sel_hi:[1,0]
	v_pk_mul_f32 v[50:51], v[50:51], v[178:179] op_sel_hi:[1,0]
	v_pk_mul_f32 v[52:53], v[52:53], v[178:179] op_sel_hi:[1,0]
	v_add_co_u32_e32 v236, vcc, 0x16000, v236
	s_nop 1
	v_addc_co_u32_e32 v237, vcc, 0, v237, vcc
	v_pk_mul_f32 v[192:193], v[54:55], s[100:101] op_sel_hi:[1,0]
	v_pk_mul_f32 v[194:195], v[56:57], s[100:101] op_sel_hi:[1,0]
	v_pk_mul_f32 v[196:197], v[50:51], s[100:101] op_sel_hi:[1,0]
	v_pk_mul_f32 v[198:199], v[52:53], s[100:101] op_sel_hi:[1,0]
	v_exp_f32_e32 v192, v192
	v_exp_f32_e32 v193, v193
	v_exp_f32_e32 v194, v194
	v_exp_f32_e32 v195, v195
	v_exp_f32_e32 v196, v196
	v_exp_f32_e32 v197, v197
	v_exp_f32_e32 v198, v198
	v_exp_f32_e32 v199, v199
	v_pk_add_f32 v[192:193], v[192:193], s[98:99] op_sel_hi:[1,0]
	v_pk_add_f32 v[194:195], v[194:195], s[98:99] op_sel_hi:[1,0]
	v_pk_add_f32 v[196:197], v[196:197], s[98:99] op_sel_hi:[1,0]
	v_pk_add_f32 v[198:199], v[198:199], s[98:99] op_sel_hi:[1,0]
	v_rcp_f32_e32 v192, v192
	v_rcp_f32_e32 v193, v193
	v_rcp_f32_e32 v194, v194
	v_rcp_f32_e32 v195, v195
	v_rcp_f32_e32 v196, v196
	v_rcp_f32_e32 v197, v197
	v_rcp_f32_e32 v198, v198
	v_rcp_f32_e32 v199, v199
	v_pk_mul_f32 v[54:55], v[54:55], v[192:193]
	v_pk_mul_f32 v[56:57], v[56:57], v[194:195]
	v_pk_mul_f32 v[50:51], v[50:51], v[196:197]
	v_pk_mul_f32 v[52:53], v[52:53], v[198:199]
	v_pk_mul_f32 v[54:55], v[54:55], s[70:71] op_sel_hi:[1,0]
	v_pk_mul_f32 v[56:57], v[56:57], s[70:71] op_sel_hi:[1,0]
	v_pk_mul_f32 v[50:51], v[50:51], s[70:71] op_sel_hi:[1,0]
	v_pk_mul_f32 v[52:53], v[52:53], s[70:71] op_sel_hi:[1,0]
	v_cvt_pk_bf16_f32 v54, v54, v55
	v_cvt_pk_bf16_f32 v55, v56, v57
	v_cvt_pk_bf16_f32 v56, v50, v51
	v_cvt_pk_bf16_f32 v57, v52, v53
	global_store_dwordx4 v[236:237], v[54:57], off offset:256
	v_pk_mul_f32 v[46:47], v[46:47], v[180:181] op_sel_hi:[1,0]
	v_pk_mul_f32 v[48:49], v[48:49], v[180:181] op_sel_hi:[1,0]
	v_pk_mul_f32 v[42:43], v[42:43], v[180:181] op_sel_hi:[1,0]
	v_pk_mul_f32 v[44:45], v[44:45], v[180:181] op_sel_hi:[1,0]
	v_add_co_u32_e32 v236, vcc, 0x16000, v236
	s_nop 1
	v_addc_co_u32_e32 v237, vcc, 0, v237, vcc
	v_pk_mul_f32 v[192:193], v[46:47], s[100:101] op_sel_hi:[1,0]
	v_pk_mul_f32 v[194:195], v[48:49], s[100:101] op_sel_hi:[1,0]
	v_pk_mul_f32 v[196:197], v[42:43], s[100:101] op_sel_hi:[1,0]
	v_pk_mul_f32 v[198:199], v[44:45], s[100:101] op_sel_hi:[1,0]
	v_exp_f32_e32 v192, v192
	v_exp_f32_e32 v193, v193
	v_exp_f32_e32 v194, v194
	v_exp_f32_e32 v195, v195
	v_exp_f32_e32 v196, v196
	v_exp_f32_e32 v197, v197
	v_exp_f32_e32 v198, v198
	v_exp_f32_e32 v199, v199
	v_pk_add_f32 v[192:193], v[192:193], s[98:99] op_sel_hi:[1,0]
	v_pk_add_f32 v[194:195], v[194:195], s[98:99] op_sel_hi:[1,0]
	v_pk_add_f32 v[196:197], v[196:197], s[98:99] op_sel_hi:[1,0]
	v_pk_add_f32 v[198:199], v[198:199], s[98:99] op_sel_hi:[1,0]
	v_rcp_f32_e32 v192, v192
	v_rcp_f32_e32 v193, v193
	v_rcp_f32_e32 v194, v194
	v_rcp_f32_e32 v195, v195
	v_rcp_f32_e32 v196, v196
	v_rcp_f32_e32 v197, v197
	v_rcp_f32_e32 v198, v198
	v_rcp_f32_e32 v199, v199
	v_pk_mul_f32 v[46:47], v[46:47], v[192:193]
	v_pk_mul_f32 v[48:49], v[48:49], v[194:195]
	v_pk_mul_f32 v[42:43], v[42:43], v[196:197]
	v_pk_mul_f32 v[44:45], v[44:45], v[198:199]
	v_pk_mul_f32 v[46:47], v[46:47], s[70:71] op_sel_hi:[1,0]
	v_pk_mul_f32 v[48:49], v[48:49], s[70:71] op_sel_hi:[1,0]
	v_pk_mul_f32 v[42:43], v[42:43], s[70:71] op_sel_hi:[1,0]
	v_pk_mul_f32 v[44:45], v[44:45], s[70:71] op_sel_hi:[1,0]
	v_cvt_pk_bf16_f32 v46, v46, v47
	v_cvt_pk_bf16_f32 v47, v48, v49
	v_cvt_pk_bf16_f32 v48, v42, v43
; __device__ __forceinline__ unsigned cvt_pk_bf16(float lo, float hi) { f32x2 v = {lo, hi}; return __builtin_bit_cast(unsigned, __builtin_convertvector(v, nbf16x2e)); }
;     __device__ __forceinline__ void operator()(const f32x4 (&acc)[2][2][4][2], const Unit& u, int wr, int wc, int fr, int fq) const {
;     ...
;                 for (int m = 0; m < 4; ++m) {
;                     const int row = row0 + ai * HALF + m * 16; const float rs = rsc ? rsc[row - rbase] : rstd[row];
;                     float v[8];
; #pragma unroll
;                     for (int i = 0; i < 4; ++i) { v[i] = acc[ai][bj][m][0][i] * rs; v[4 + i] = acc[ai][bj][m][1][i] * rs; }
;                     if (seg == 0) {
; #pragma unroll
;                         for (int i = 0; i < 8; ++i) v[i] = v[i] * __builtin_amdgcn_rcpf(1.0f + __expf(-v[i])) * 0.08838834764831845f;
;                     } else if (seg == 1) {
; #pragma unroll
;                         for (int i = 0; i < 8; ++i) { const float s = __builtin_amdgcn_rcpf(1.0f + __expf(-v[i])); v[i] = __logf(lb[i] + (1.0f - lb[i]) * s); }
;                     } else if (seg == 3) {
; #pragma unroll
;                         for (int i = 0; i < 8; ++i) v[i] = v[i] * __builtin_amdgcn_rcpf(1.0f + __expf(-v[i]));
;                     }
;                     u32x4 w; w.x = cvt_pk_bf16(v[0], v[1]); w.y = cvt_pk_bf16(v[2], v[3]); w.z = cvt_pk_bf16(v[4], v[5]); w.w = cvt_pk_bf16(v[6], v[7]);
;                     *(u32x4*)(O + (size_t)row * 2816 + col0) = w;
	v_cvt_pk_bf16_f32 v49, v44, v45
	global_store_dwordx4 v[236:237], v[46:49], off offset:256
	v_pk_mul_f32 v[38:39], v[38:39], v[182:183] op_sel_hi:[1,0]
	v_pk_mul_f32 v[40:41], v[40:41], v[182:183] op_sel_hi:[1,0]
	v_pk_mul_f32 v[34:35], v[34:35], v[182:183] op_sel_hi:[1,0]
	v_pk_mul_f32 v[36:37], v[36:37], v[182:183] op_sel_hi:[1,0]
	v_add_co_u32_e32 v236, vcc, 0x16000, v236
	s_nop 1
	v_addc_co_u32_e32 v237, vcc, 0, v237, vcc
	v_pk_mul_f32 v[192:193], v[38:39], s[100:101] op_sel_hi:[1,0]
	v_pk_mul_f32 v[194:195], v[40:41], s[100:101] op_sel_hi:[1,0]
	v_pk_mul_f32 v[196:197], v[34:35], s[100:101] op_sel_hi:[1,0]
	v_pk_mul_f32 v[198:199], v[36:37], s[100:101] op_sel_hi:[1,0]
	v_exp_f32_e32 v192, v192
	v_exp_f32_e32 v193, v193
	v_exp_f32_e32 v194, v194
	v_exp_f32_e32 v195, v195
	v_exp_f32_e32 v196, v196
	v_exp_f32_e32 v197, v197
	v_exp_f32_e32 v198, v198
	v_exp_f32_e32 v199, v199
	v_pk_add_f32 v[192:193], v[192:193], s[98:99] op_sel_hi:[1,0]
	v_pk_add_f32 v[194:195], v[194:195], s[98:99] op_sel_hi:[1,0]
	v_pk_add_f32 v[196:197], v[196:197], s[98:99] op_sel_hi:[1,0]
	v_pk_add_f32 v[198:199], v[198:199], s[98:99] op_sel_hi:[1,0]
	v_rcp_f32_e32 v192, v192
	v_rcp_f32_e32 v193, v193
	v_rcp_f32_e32 v194, v194
	v_rcp_f32_e32 v195, v195
	v_rcp_f32_e32 v196, v196
	v_rcp_f32_e32 v197, v197
	v_rcp_f32_e32 v198, v198
	v_rcp_f32_e32 v199, v199
	v_pk_mul_f32 v[38:39], v[38:39], v[192:193]
	v_pk_mul_f32 v[40:41], v[40:41], v[194:195]
	v_pk_mul_f32 v[34:35], v[34:35], v[196:197]
	v_pk_mul_f32 v[36:37], v[36:37], v[198:199]
	v_pk_mul_f32 v[38:39], v[38:39], s[70:71] op_sel_hi:[1,0]
	v_pk_mul_f32 v[40:41], v[40:41], s[70:71] op_sel_hi:[1,0]
	v_pk_mul_f32 v[34:35], v[34:35], s[70:71] op_sel_hi:[1,0]
	v_pk_mul_f32 v[36:37], v[36:37], s[70:71] op_sel_hi:[1,0]
	v_cvt_pk_bf16_f32 v38, v38, v39
	v_cvt_pk_bf16_f32 v39, v40, v41
	v_cvt_pk_bf16_f32 v40, v34, v35
	v_cvt_pk_bf16_f32 v41, v36, v37
	global_store_dwordx4 v[236:237], v[38:41], off offset:256
	v_pk_mul_f32 v[30:31], v[30:31], v[184:185] op_sel_hi:[1,0]
	v_pk_mul_f32 v[32:33], v[32:33], v[184:185] op_sel_hi:[1,0]
	v_pk_mul_f32 v[26:27], v[26:27], v[184:185] op_sel_hi:[1,0]
	v_pk_mul_f32 v[28:29], v[28:29], v[184:185] op_sel_hi:[1,0]
	v_add_co_u32_e32 v236, vcc, 0x6e000, v236
	s_nop 1
	v_addc_co_u32_e32 v237, vcc, 0, v237, vcc
	v_pk_mul_f32 v[192:193], v[30:31], s[100:101] op_sel_hi:[1,0]
	v_pk_mul_f32 v[194:195], v[32:33], s[100:101] op_sel_hi:[1,0]
	v_pk_mul_f32 v[196:197], v[26:27], s[100:101] op_sel_hi:[1,0]
	v_pk_mul_f32 v[198:199], v[28:29], s[100:101] op_sel_hi:[1,0]
	v_exp_f32_e32 v192, v192
	v_exp_f32_e32 v193, v193
	v_exp_f32_e32 v194, v194
	v_exp_f32_e32 v195, v195
	v_exp_f32_e32 v196, v196
	v_exp_f32_e32 v197, v197
	v_exp_f32_e32 v198, v198
	v_exp_f32_e32 v199, v199
	v_pk_add_f32 v[192:193], v[192:193], s[98:99] op_sel_hi:[1,0]
	v_pk_add_f32 v[194:195], v[194:195], s[98:99] op_sel_hi:[1,0]
	v_pk_add_f32 v[196:197], v[196:197], s[98:99] op_sel_hi:[1,0]
	v_pk_add_f32 v[198:199], v[198:199], s[98:99] op_sel_hi:[1,0]
	v_rcp_f32_e32 v192, v192
	v_rcp_f32_e32 v193, v193
	v_rcp_f32_e32 v194, v194
	v_rcp_f32_e32 v195, v195
	v_rcp_f32_e32 v196, v196
	v_rcp_f32_e32 v197, v197
	v_rcp_f32_e32 v198, v198
	v_rcp_f32_e32 v199, v199
	v_pk_mul_f32 v[30:31], v[30:31], v[192:193]
	v_pk_mul_f32 v[32:33], v[32:33], v[194:195]
	v_pk_mul_f32 v[26:27], v[26:27], v[196:197]
	v_pk_mul_f32 v[28:29], v[28:29], v[198:199]
	v_pk_mul_f32 v[30:31], v[30:31], s[70:71] op_sel_hi:[1,0]
	v_pk_mul_f32 v[32:33], v[32:33], s[70:71] op_sel_hi:[1,0]
	v_pk_mul_f32 v[26:27], v[26:27], s[70:71] op_sel_hi:[1,0]
	v_pk_mul_f32 v[28:29], v[28:29], s[70:71] op_sel_hi:[1,0]
	v_cvt_pk_bf16_f32 v30, v30, v31
	v_cvt_pk_bf16_f32 v31, v32, v33
	v_cvt_pk_bf16_f32 v32, v26, v27
	v_cvt_pk_bf16_f32 v33, v28, v29
	global_store_dwordx4 v[236:237], v[30:33], off offset:256
	v_pk_mul_f32 v[22:23], v[22:23], v[186:187] op_sel_hi:[1,0]
	v_pk_mul_f32 v[24:25], v[24:25], v[186:187] op_sel_hi:[1,0]
	v_pk_mul_f32 v[18:19], v[18:19], v[186:187] op_sel_hi:[1,0]
	v_pk_mul_f32 v[20:21], v[20:21], v[186:187] op_sel_hi:[1,0]
	v_add_co_u32_e32 v236, vcc, 0x16000, v236
	s_nop 1
	v_addc_co_u32_e32 v237, vcc, 0, v237, vcc
	v_pk_mul_f32 v[192:193], v[22:23], s[100:101] op_sel_hi:[1,0]
	v_pk_mul_f32 v[194:195], v[24:25], s[100:101] op_sel_hi:[1,0]
	v_pk_mul_f32 v[196:197], v[18:19], s[100:101] op_sel_hi:[1,0]
	v_pk_mul_f32 v[198:199], v[20:21], s[100:101] op_sel_hi:[1,0]
	v_exp_f32_e32 v192, v192
	v_exp_f32_e32 v193, v193
	v_exp_f32_e32 v194, v194
	v_exp_f32_e32 v195, v195
	v_exp_f32_e32 v196, v196
	v_exp_f32_e32 v197, v197
	v_exp_f32_e32 v198, v198
	v_exp_f32_e32 v199, v199
	v_pk_add_f32 v[192:193], v[192:193], s[98:99] op_sel_hi:[1,0]
; __device__ __forceinline__ unsigned cvt_pk_bf16(float lo, float hi) { f32x2 v = {lo, hi}; return __builtin_bit_cast(unsigned, __builtin_convertvector(v, nbf16x2e)); }
;     __device__ __forceinline__ void operator()(const f32x4 (&acc)[2][2][4][2], const Unit& u, int wr, int wc, int fr, int fq) const {
;     ...
;                 for (int m = 0; m < 4; ++m) {
;                     const int row = row0 + ai * HALF + m * 16; const float rs = rsc ? rsc[row - rbase] : rstd[row];
;                     float v[8];
; #pragma unroll
;                     for (int i = 0; i < 4; ++i) { v[i] = acc[ai][bj][m][0][i] * rs; v[4 + i] = acc[ai][bj][m][1][i] * rs; }
;                     if (seg == 0) {
; #pragma unroll
;                         for (int i = 0; i < 8; ++i) v[i] = v[i] * __builtin_amdgcn_rcpf(1.0f + __expf(-v[i])) * 0.08838834764831845f;
;                     } else if (seg == 1) {
; #pragma unroll
;                         for (int i = 0; i < 8; ++i) { const float s = __builtin_amdgcn_rcpf(1.0f + __expf(-v[i])); v[i] = __logf(lb[i] + (1.0f - lb[i]) * s); }
;                     } else if (seg == 3) {
; #pragma unroll
;                         for (int i = 0; i < 8; ++i) v[i] = v[i] * __builtin_amdgcn_rcpf(1.0f + __expf(-v[i]));
;                     }
;                     u32x4 w; w.x = cvt_pk_bf16(v[0], v[1]); w.y = cvt_pk_bf16(v[2], v[3]); w.z = cvt_pk_bf16(v[4], v[5]); w.w = cvt_pk_bf16(v[6], v[7]);
;                     *(u32x4*)(O + (size_t)row * 2816 + col0) = w;
	v_pk_add_f32 v[194:195], v[194:195], s[98:99] op_sel_hi:[1,0]
	v_pk_add_f32 v[196:197], v[196:197], s[98:99] op_sel_hi:[1,0]
	v_pk_add_f32 v[198:199], v[198:199], s[98:99] op_sel_hi:[1,0]
	v_rcp_f32_e32 v192, v192
	v_rcp_f32_e32 v193, v193
	v_rcp_f32_e32 v194, v194
	v_rcp_f32_e32 v195, v195
	v_rcp_f32_e32 v196, v196
	v_rcp_f32_e32 v197, v197
	v_rcp_f32_e32 v198, v198
	v_rcp_f32_e32 v199, v199
	v_pk_mul_f32 v[22:23], v[22:23], v[192:193]
	v_pk_mul_f32 v[24:25], v[24:25], v[194:195]
	v_pk_mul_f32 v[18:19], v[18:19], v[196:197]
	v_pk_mul_f32 v[20:21], v[20:21], v[198:199]
	v_pk_mul_f32 v[22:23], v[22:23], s[70:71] op_sel_hi:[1,0]
	v_pk_mul_f32 v[24:25], v[24:25], s[70:71] op_sel_hi:[1,0]
	v_pk_mul_f32 v[18:19], v[18:19], s[70:71] op_sel_hi:[1,0]
	v_pk_mul_f32 v[20:21], v[20:21], s[70:71] op_sel_hi:[1,0]
	v_cvt_pk_bf16_f32 v22, v22, v23
	v_cvt_pk_bf16_f32 v23, v24, v25
	v_cvt_pk_bf16_f32 v24, v18, v19
	v_cvt_pk_bf16_f32 v25, v20, v21
	global_store_dwordx4 v[236:237], v[22:25], off offset:256
	v_pk_mul_f32 v[14:15], v[14:15], v[188:189] op_sel_hi:[1,0]
	v_pk_mul_f32 v[16:17], v[16:17], v[188:189] op_sel_hi:[1,0]
	v_pk_mul_f32 v[10:11], v[10:11], v[188:189] op_sel_hi:[1,0]
	v_pk_mul_f32 v[12:13], v[12:13], v[188:189] op_sel_hi:[1,0]
	v_add_co_u32_e32 v236, vcc, 0x16000, v236
	s_nop 1
	v_addc_co_u32_e32 v237, vcc, 0, v237, vcc
	v_pk_mul_f32 v[192:193], v[14:15], s[100:101] op_sel_hi:[1,0]
	v_pk_mul_f32 v[194:195], v[16:17], s[100:101] op_sel_hi:[1,0]
	v_pk_mul_f32 v[196:197], v[10:11], s[100:101] op_sel_hi:[1,0]
	v_pk_mul_f32 v[198:199], v[12:13], s[100:101] op_sel_hi:[1,0]
	v_exp_f32_e32 v192, v192
	v_exp_f32_e32 v193, v193
	v_exp_f32_e32 v194, v194
	v_exp_f32_e32 v195, v195
	v_exp_f32_e32 v196, v196
	v_exp_f32_e32 v197, v197
	v_exp_f32_e32 v198, v198
	v_exp_f32_e32 v199, v199
	v_pk_add_f32 v[192:193], v[192:193], s[98:99] op_sel_hi:[1,0]
	v_pk_add_f32 v[194:195], v[194:195], s[98:99] op_sel_hi:[1,0]
	v_pk_add_f32 v[196:197], v[196:197], s[98:99] op_sel_hi:[1,0]
	v_pk_add_f32 v[198:199], v[198:199], s[98:99] op_sel_hi:[1,0]
	v_rcp_f32_e32 v192, v192
	v_rcp_f32_e32 v193, v193
	v_rcp_f32_e32 v194, v194
	v_rcp_f32_e32 v195, v195
	v_rcp_f32_e32 v196, v196
	v_rcp_f32_e32 v197, v197
	v_rcp_f32_e32 v198, v198
	v_rcp_f32_e32 v199, v199
	v_pk_mul_f32 v[14:15], v[14:15], v[192:193]
	v_pk_mul_f32 v[16:17], v[16:17], v[194:195]
	v_pk_mul_f32 v[10:11], v[10:11], v[196:197]
	v_pk_mul_f32 v[12:13], v[12:13], v[198:199]
	v_pk_mul_f32 v[14:15], v[14:15], s[70:71] op_sel_hi:[1,0]
	v_pk_mul_f32 v[16:17], v[16:17], s[70:71] op_sel_hi:[1,0]
	v_pk_mul_f32 v[10:11], v[10:11], s[70:71] op_sel_hi:[1,0]
	v_pk_mul_f32 v[12:13], v[12:13], s[70:71] op_sel_hi:[1,0]
	v_cvt_pk_bf16_f32 v14, v14, v15
	v_cvt_pk_bf16_f32 v15, v16, v17
	v_cvt_pk_bf16_f32 v16, v10, v11
	v_cvt_pk_bf16_f32 v17, v12, v13
	global_store_dwordx4 v[236:237], v[14:17], off offset:256
	v_pk_mul_f32 v[6:7], v[6:7], v[190:191] op_sel_hi:[1,0]
	v_pk_mul_f32 v[8:9], v[8:9], v[190:191] op_sel_hi:[1,0]
	v_pk_mul_f32 v[2:3], v[2:3], v[190:191] op_sel_hi:[1,0]
	v_pk_mul_f32 v[4:5], v[4:5], v[190:191] op_sel_hi:[1,0]
	v_add_co_u32_e32 v236, vcc, 0x16000, v236
	s_nop 1
	v_addc_co_u32_e32 v237, vcc, 0, v237, vcc
	v_pk_mul_f32 v[192:193], v[6:7], s[100:101] op_sel_hi:[1,0]
	v_pk_mul_f32 v[194:195], v[8:9], s[100:101] op_sel_hi:[1,0]
	v_pk_mul_f32 v[196:197], v[2:3], s[100:101] op_sel_hi:[1,0]
	v_pk_mul_f32 v[198:199], v[4:5], s[100:101] op_sel_hi:[1,0]
	v_exp_f32_e32 v192, v192
	v_exp_f32_e32 v193, v193
	v_exp_f32_e32 v194, v194
	v_exp_f32_e32 v195, v195
	v_exp_f32_e32 v196, v196
	v_exp_f32_e32 v197, v197
	v_exp_f32_e32 v198, v198
	v_exp_f32_e32 v199, v199
	v_pk_add_f32 v[192:193], v[192:193], s[98:99] op_sel_hi:[1,0]
	v_pk_add_f32 v[194:195], v[194:195], s[98:99] op_sel_hi:[1,0]
	v_pk_add_f32 v[196:197], v[196:197], s[98:99] op_sel_hi:[1,0]
	v_pk_add_f32 v[198:199], v[198:199], s[98:99] op_sel_hi:[1,0]
	v_rcp_f32_e32 v192, v192
	v_rcp_f32_e32 v193, v193
	v_rcp_f32_e32 v194, v194
	v_rcp_f32_e32 v195, v195
	v_rcp_f32_e32 v196, v196
	v_rcp_f32_e32 v197, v197
	v_rcp_f32_e32 v198, v198
	v_rcp_f32_e32 v199, v199
	v_pk_mul_f32 v[6:7], v[6:7], v[192:193]
	v_pk_mul_f32 v[8:9], v[8:9], v[194:195]
	v_pk_mul_f32 v[2:3], v[2:3], v[196:197]
	v_pk_mul_f32 v[4:5], v[4:5], v[198:199]
	v_pk_mul_f32 v[6:7], v[6:7], s[70:71] op_sel_hi:[1,0]
	v_pk_mul_f32 v[8:9], v[8:9], s[70:71] op_sel_hi:[1,0]
	v_pk_mul_f32 v[2:3], v[2:3], s[70:71] op_sel_hi:[1,0]
	v_pk_mul_f32 v[4:5], v[4:5], s[70:71] op_sel_hi:[1,0]
	v_cvt_pk_bf16_f32 v6, v6, v7
	v_cvt_pk_bf16_f32 v7, v8, v9
	v_cvt_pk_bf16_f32 v8, v2, v3
	v_cvt_pk_bf16_f32 v9, v4, v5
	global_store_dwordx4 v[236:237], v[6:9], off offset:256
	s_andn2_b64 vcc, exec, s[4:5]
	s_mov_b64 s[0:1], -1
	s_branch .Lep_done
